# v5: LN1+router row loop (4 phases): row prefetch stays in flight across the iteration end via fresh registers and counted vmcnt(8); flat ops of the loop converted to global
# baseline (speedup 1.0000x reference)
.LBB0_455:
	s_or_b64 exec, exec, s[18:19]
	s_lshl_b32 s0, s39, 8
	s_add_i32 s0, s0, s97
	s_ashr_i32 s1, s0, 31
	s_lshl_b64 s[18:19], s[0:1], 11
	v_lshl_add_u64 v[38:39], v[54:55], 0, s[18:19]
	v_add_co_u32_e32 v44, vcc, 0x4000, v38
	s_waitcnt lgkmcnt(0)
	s_barrier
	global_load_dwordx4 v[2:5], v[50:51], off
	global_load_dwordx4 v[6:9], v[50:51], off offset:1024
	global_load_dwordx4 v[10:13], v[52:53], off
	global_load_dwordx4 v[14:17], v[52:53], off offset:1024
	global_load_dwordx4 v[18:21], v[50:51], off offset:2048
	global_load_dwordx4 v[22:25], v[50:51], off offset:3072
	global_load_dwordx4 v[26:29], v[52:53], off offset:2048
	global_load_dwordx4 v[30:33], v[52:53], off offset:3072
	v_lshl_add_u64 v[42:43], v[38:39], 0, s[28:29]
	v_addc_co_u32_e32 v45, vcc, 0, v39, vcc
	global_load_dwordx2 v[36:37], v[38:39], off
	global_load_dwordx2 v[34:35], v[38:39], off offset:512
	global_load_dwordx2 v[40:41], v[38:39], off offset:1024
	s_nop 0
	global_load_dwordx2 v[38:39], v[38:39], off offset:1536
	s_nop 0
	global_load_dwordx2 v[60:61], v[44:45], off
	global_load_dwordx2 v[62:63], v[42:43], off offset:512
	global_load_dwordx2 v[64:65], v[42:43], off offset:1024
	global_load_dwordx2 v[66:67], v[42:43], off offset:1536
	s_mov_b32 s34, 0
	s_add_i32 s35, s0, 16
	s_mov_b32 s36, 0
	s_waitcnt vmcnt(0)
	v_mov_b64_e32 v[224:225], v[60:61]
	v_mov_b64_e32 v[226:227], v[62:63]
	v_mov_b64_e32 v[228:229], v[64:65]
	v_mov_b64_e32 v[230:231], v[66:67]
	s_branch .LBB0_458

.LBB0_457:
	s_add_i32 s36, s36, 1
	s_add_i32 s34, s34, 8
	s_cmpk_lg_i32 s34, 0x100
	v_mov_b64_e32 v[38:39], v[66:67]
	v_mov_b64_e32 v[40:41], v[64:65]
	v_mov_b64_e32 v[34:35], v[62:63]
	v_mov_b64_e32 v[36:37], v[60:61]
	s_waitcnt lgkmcnt(0)
	s_cbranch_scc0 .LBB0_441
.LBB0_458:
	s_waitcnt lgkmcnt(0)
	v_lshlrev_b32_e32 v85, 16, v37
	v_lshlrev_b32_e32 v84, 16, v36
	v_and_b32_e32 v37, 0xffff0000, v37
	v_and_b32_e32 v36, 0xffff0000, v36
	v_pk_add_f32 v[68:69], v[84:85], v[36:37]
	v_lshlrev_b32_e32 v87, 16, v35
	v_lshlrev_b32_e32 v86, 16, v34
	v_and_b32_e32 v35, 0xffff0000, v35
	v_and_b32_e32 v34, 0xffff0000, v34
	v_lshlrev_b32_e32 v46, 16, v39
	v_and_b32_e32 v48, 0xffff0000, v39
	v_add_f32_e32 v39, v68, v69
	v_pk_add_f32 v[68:69], v[86:87], v[34:35]
	v_lshlrev_b32_e32 v42, 16, v40
	v_and_b32_e32 v43, 0xffff0000, v40
	v_lshlrev_b32_e32 v40, 16, v41
	v_and_b32_e32 v41, 0xffff0000, v41
	v_pk_add_f32 v[68:69], v[68:69], v[68:69] op_sel_hi:[0,1]
	v_lshlrev_b32_e32 v44, 16, v38
	v_and_b32_e32 v38, 0xffff0000, v38
	v_add_f32_e32 v49, 0, v39
	v_add_f32_e32 v45, v42, v43
	v_add_f32_e32 v39, v40, v41
	v_mov_b32_e32 v47, v69
	v_pk_add_f32 v[70:71], v[44:45], v[38:39]
	v_pk_add_f32 v[68:69], v[46:47], v[48:49]
	s_min_u32 s0, s36, 29
	v_pk_add_f32 v[68:69], v[70:71], v[68:69]
	s_lshl_b32 s0, s0, 3
	v_add_f32_e32 v39, v68, v69
	s_add_i32 s18, s35, s0
	s_nop 0
	v_add_f32_dpp v39, v39, v39 quad_perm:[1,0,3,2] row_mask:0xf bank_mask:0xf bound_ctrl:1
	s_nop 1
	v_add_f32_dpp v39, v39, v39 quad_perm:[2,3,0,1] row_mask:0xf bank_mask:0xf bound_ctrl:1
	s_nop 1
	v_add_f32_dpp v39, v39, v39 row_half_mirror row_mask:0xf bank_mask:0xf bound_ctrl:1
	s_nop 1
	v_add_f32_dpp v39, v39, v39 row_mirror row_mask:0xf bank_mask:0xf bound_ctrl:1
	s_nop 0
	v_readlane_b32 s19, v39, 16
	v_readlane_b32 s20, v39, 48
	v_readlane_b32 s0, v39, 0
	v_readlane_b32 s1, v39, 32
	v_mov_b32_e32 v68, s19
	v_mov_b32_e32 v69, s20
	v_pk_add_f32 v[68:69], s[0:1], v[68:69]
	s_nop 0
	v_add_f32_e32 v39, v68, v69
	v_fmac_f32_e32 v36, 0xba800000, v39
	v_fmac_f32_e32 v37, 0xba800000, v39
	v_fmac_f32_e32 v85, 0xba800000, v39
	v_fmac_f32_e32 v84, 0xba800000, v39
	v_mov_b32_e32 v88, v85
	v_mov_b32_e32 v89, v37
	v_mov_b32_e32 v85, v36
	v_fmac_f32_e32 v34, 0xba800000, v39
	v_fmac_f32_e32 v35, 0xba800000, v39
	v_fmac_f32_e32 v87, 0xba800000, v39
	v_pk_mul_f32 v[68:69], v[88:89], v[88:89]
	v_pk_mul_f32 v[36:37], v[84:85], v[84:85]
	v_fmac_f32_e32 v86, 0xba800000, v39
	v_mov_b32_e32 v90, v87
	v_mov_b32_e32 v91, v35
	v_mov_b32_e32 v87, v34
	v_pk_mov_b32 v[70:71], v[36:37], v[68:69] op_sel:[1,0]
	v_mov_b32_e32 v37, v69
	v_pk_mul_f32 v[68:69], v[90:91], v[90:91]
	v_pk_mul_f32 v[34:35], v[86:87], v[86:87]
	v_pk_add_f32 v[36:37], v[70:71], v[36:37]
	v_pk_mov_b32 v[70:71], v[34:35], v[68:69] op_sel:[1,0]
	v_mov_b32_e32 v35, v69
	v_pk_add_f32 v[34:35], v[70:71], v[34:35]
	v_fmac_f32_e32 v42, 0xba800000, v39
	v_pk_add_f32 v[34:35], v[34:35], v[34:35] op_sel_hi:[0,1]
	v_fmac_f32_e32 v43, 0xba800000, v39
	v_fmac_f32_e32 v40, 0xba800000, v39
	v_mul_f32_e32 v34, v42, v42
	v_fmac_f32_e32 v41, 0xba800000, v39
	v_pk_fma_f32 v[68:69], v[42:43], v[42:43], v[34:35] op_sel_hi:[1,1,0]
	v_mul_f32_e32 v34, v40, v40
	v_pk_add_f32 v[36:37], v[36:37], v[36:37] op_sel_hi:[0,1]
	v_pk_fma_f32 v[70:71], v[40:41], v[40:41], v[34:35] op_sel_hi:[1,1,0]
	v_fmac_f32_e32 v48, 0xba800000, v39
	v_fmac_f32_e32 v46, 0xba800000, v39
	v_fmac_f32_e32 v38, 0xba800000, v39
	v_fmac_f32_e32 v44, 0xba800000, v39
	v_mul_f32_e32 v68, v44, v44
	v_mul_f32_e32 v70, v38, v38
	v_mul_f32_e32 v36, v46, v46
	v_mul_f32_e32 v34, v48, v48
	v_pk_add_f32 v[68:69], v[68:69], v[70:71]
	v_pk_add_f32 v[34:35], v[36:37], v[34:35]
	v_mov_b32_e32 v47, v48
	v_pk_add_f32 v[34:35], v[68:69], v[34:35]
	s_nop 0
	v_add_f32_e32 v34, v34, v35
	s_nop 1
	v_add_f32_dpp v34, v34, v34 quad_perm:[1,0,3,2] row_mask:0xf bank_mask:0xf bound_ctrl:1
	s_nop 1
	v_add_f32_dpp v34, v34, v34 quad_perm:[2,3,0,1] row_mask:0xf bank_mask:0xf bound_ctrl:1
	s_nop 1
	v_add_f32_dpp v34, v34, v34 row_half_mirror row_mask:0xf bank_mask:0xf bound_ctrl:1
	s_nop 1
	v_add_f32_dpp v34, v34, v34 row_mirror row_mask:0xf bank_mask:0xf bound_ctrl:1
	s_nop 0
	v_readlane_b32 s19, v34, 16
	v_readlane_b32 s20, v34, 48
	v_readlane_b32 s0, v34, 0
	v_readlane_b32 s1, v34, 32
	v_mov_b32_e32 v34, s19
	v_mov_b32_e32 v35, s20
	v_pk_add_f32 v[34:35], s[0:1], v[34:35]
	s_ashr_i32 s19, s18, 31
	v_add_f32_e32 v34, v34, v35
	v_fmamk_f32 v34, v34, 0x3a800000, v80
	v_mul_f32_e32 v35, 0x4f800000, v34
	v_cmp_gt_f32_e32 vcc, s7, v34
	s_lshl_b64 s[0:1], s[18:19], 11
	s_and_b32 s20, s36, 3
	v_cndmask_b32_e32 v36, v34, v35, vcc
	v_lshl_add_u64 v[34:35], v[54:55], 0, s[0:1]
	s_waitcnt vmcnt(8)
	v_mov_b64_e32 v[66:67], v[230:231]
	v_mov_b64_e32 v[64:65], v[228:229]
	v_mov_b64_e32 v[62:63], v[226:227]
	v_mov_b64_e32 v[60:61], v[224:225]
	global_load_dwordx2 v[224:225], v[34:35], off
	global_load_dwordx2 v[226:227], v[34:35], off offset:512
	global_load_dwordx2 v[228:229], v[34:35], off offset:1024
	global_load_dwordx2 v[230:231], v[34:35], off offset:1536
	v_sqrt_f32_e32 v37, v36
	s_mul_i32 s30, s20, 0x810
	s_add_i32 s30, s87, s30
	v_add_u32_e32 v39, -1, v37
	v_fma_f32 v45, -v39, v37, v36
	v_cmp_ge_f32_e64 s[18:19], 0, v45
	v_add_u32_e32 v45, 1, v37
	s_nop 0
	v_cndmask_b32_e64 v39, v37, v39, s[18:19]
	v_fma_f32 v37, -v45, v37, v36
	v_cmp_lt_f32_e64 s[18:19], 0, v37
	s_nop 1
	v_cndmask_b32_e64 v37, v39, v45, s[18:19]
	v_mul_f32_e32 v39, 0x37800000, v37
	v_cndmask_b32_e32 v37, v37, v39, vcc
	v_cmp_class_f32_e32 vcc, v36, v81
	s_add_i32 s18, s4, s34
	s_ashr_i32 s19, s18, 31
	v_cndmask_b32_e32 v36, v37, v36, vcc
	v_div_scale_f32 v37, s[0:1], v36, v36, 1.0
	v_rcp_f32_e32 v39, v37
	s_lshl_b64 s[0:1], s[18:19], 11
	v_fma_f32 v34, -v37, v39, 1.0
	v_fmac_f32_e32 v39, v34, v39
	v_div_scale_f32 v34, vcc, 1.0, v36, 1.0
	v_mul_f32_e32 v35, v34, v39
	v_fma_f32 v45, -v37, v35, v34
	v_fmac_f32_e32 v35, v45, v39
	v_fma_f32 v34, -v37, v35, v34
	v_div_fmas_f32 v34, v34, v39, v35
	v_div_fixup_f32 v34, v34, v36, 1.0
	v_mov_b32_e32 v45, v38
	v_pk_mul_f32 v[36:37], v[84:85], v[34:35] op_sel_hi:[1,0]
	v_pk_mul_f32 v[84:85], v[88:89], v[34:35] op_sel_hi:[1,0]
	v_pk_mul_f32 v[38:39], v[44:45], v[34:35] op_sel_hi:[1,0]
	v_mov_b32_e32 v44, v150
	v_pk_fma_f32 v[84:85], v[4:5], v[84:85], v[12:13]
	v_pk_fma_f32 v[36:37], v[2:3], v[36:37], v[10:11]
	v_pk_mul_f32 v[86:87], v[86:87], v[34:35] op_sel_hi:[1,0]
	v_pk_mul_f32 v[88:89], v[90:91], v[34:35] op_sel_hi:[1,0]
	v_pk_fma_f32 v[86:87], v[6:7], v[86:87], v[14:15]
	v_pk_fma_f32 v[88:89], v[8:9], v[88:89], v[16:17]
	v_pk_mul_f32 v[42:43], v[42:43], v[34:35] op_sel_hi:[1,0]
	v_pk_mul_f32 v[40:41], v[40:41], v[34:35] op_sel_hi:[1,0]
	v_pk_mul_f32 v[34:35], v[46:47], v[34:35] op_sel_hi:[1,0]
	v_lshl_add_u32 v48, v44, 3, s30
	v_cvt_pk_bf16_f32 v44, v36, v37
	v_cvt_pk_bf16_f32 v45, v84, v85
	v_lshl_add_u64 v[46:47], v[56:57], 0, s[0:1]
	v_pk_fma_f32 v[40:41], v[20:21], v[40:41], v[28:29]
	v_pk_fma_f32 v[42:43], v[18:19], v[42:43], v[26:27]
	global_store_dwordx2 v[46:47], v[44:45], off
	ds_write_b64 v48, v[44:45] offset:33024
	v_cvt_pk_bf16_f32 v44, v86, v87
	v_cvt_pk_bf16_f32 v45, v88, v89
	v_pk_fma_f32 v[34:35], v[24:25], v[34:35], v[32:33]
	v_pk_fma_f32 v[38:39], v[22:23], v[38:39], v[30:31]
	global_store_dwordx2 v[46:47], v[44:45], off offset:512
	ds_write_b64 v48, v[44:45] offset:33536
	v_cvt_pk_bf16_f32 v44, v42, v43
	v_cvt_pk_bf16_f32 v45, v40, v41
	global_store_dwordx2 v[46:47], v[44:45], off offset:1024
	ds_write_b64 v48, v[44:45] offset:34048
	v_cvt_pk_bf16_f32 v44, v38, v39
	v_cvt_pk_bf16_f32 v45, v34, v35
	global_store_dwordx2 v[46:47], v[44:45], off offset:1536
	ds_write_b64 v48, v[44:45] offset:34560
	v_med3_f32 v36, v36, s38, v82
	v_med3_f32 v37, v37, s38, v82
	v_mov_b32_e32 v44, 0
	v_cvt_pk_fp8_f32 v44, v36, v37
	v_med3_f32 v36, v84, s38, v82
	v_med3_f32 v37, v85, s38, v82
	v_med3_f32 v45, v86, s38, v82
	v_cvt_pk_fp8_f32 v44, v36, v37 op_sel:[0,0,1]
	v_med3_f32 v46, v87, s38, v82
	v_mov_b32_e32 v47, 0
	v_cvt_pk_fp8_f32 v47, v45, v46
	s_lshl_b64 s[0:1], s[18:19], 10
	v_lshl_add_u64 v[36:37], v[58:59], 0, s[0:1]
	global_store_dword v[36:37], v44, off
	v_med3_f32 v44, v88, s38, v82
	v_med3_f32 v45, v89, s38, v82
	v_cvt_pk_fp8_f32 v47, v44, v45 op_sel:[0,0,1]
	v_med3_f32 v42, v42, s38, v82
	v_med3_f32 v43, v43, s38, v82
	v_mov_b32_e32 v44, 0
	v_cvt_pk_fp8_f32 v44, v42, v43
	v_med3_f32 v38, v38, s38, v82
	v_med3_f32 v39, v39, s38, v82
	v_mov_b32_e32 v42, 0
	v_cvt_pk_fp8_f32 v42, v38, v39
	v_med3_f32 v34, v34, s38, v82
	v_med3_f32 v35, v35, s38, v82
	v_med3_f32 v40, v40, s38, v82
	v_med3_f32 v41, v41, s38, v82
	v_cvt_pk_fp8_f32 v42, v34, v35 op_sel:[0,0,1]
	v_cvt_pk_fp8_f32 v44, v40, v41 op_sel:[0,0,1]
	s_cmp_lg_u32 s20, 3
	global_store_dword v[36:37], v47, off offset:256
	global_store_dword v[36:37], v44, off offset:512
	global_store_dword v[36:37], v42, off offset:768
	s_cbranch_scc1 .LBB0_457
	v_mov_b32_e32 v100, v150
	s_nop 0
	v_and_b32_e32 v34, 3, v100
	v_mul_u32_u24_e32 v34, 0x810, v34
	v_and_b32_e32 v38, -16, v100
	v_add3_u32 v83, s87, v34, v38
	ds_read_b128 v[34:37], v83 offset:33024
	v_and_b32_e32 v39, 15, v100
	v_mul_u32_u24_e32 v39, 0x810, v39
	v_add3_u32 v101, 0, v39, v38
	ds_read_b128 v[38:41], v83 offset:33088
	ds_read_b128 v[42:45], v101
	ds_read_b128 v[46:49], v101 offset:64
	s_waitcnt lgkmcnt(0)
	v_mfma_f32_16x16x32_bf16 v[38:41], v[38:41], v[46:49], 0
	v_cmp_gt_i32_e32 vcc, 16, v100
	v_mfma_f32_16x16x32_bf16 v[34:37], v[34:37], v[42:45], 0
	ds_read_b128 v[42:45], v83 offset:33152
	ds_read_b128 v[46:49], v83 offset:33216
	ds_read_b128 v[84:87], v101 offset:128
	ds_read_b128 v[88:91], v101 offset:192
	s_waitcnt lgkmcnt(0)
	v_mfma_f32_16x16x32_bf16 v[42:45], v[42:45], v[84:87], 0
	ds_read_b128 v[84:87], v83 offset:33280
	v_mfma_f32_16x16x32_bf16 v[46:49], v[46:49], v[88:91], 0
	ds_read_b128 v[88:91], v83 offset:33344
	ds_read_b128 v[92:95], v101 offset:256
	ds_read_b128 v[96:99], v101 offset:320
	s_waitcnt lgkmcnt(0)
	v_mfma_f32_16x16x32_bf16 v[34:37], v[84:87], v[92:95], v[34:37]
	ds_read_b128 v[84:87], v83 offset:33408
	v_mfma_f32_16x16x32_bf16 v[38:41], v[88:91], v[96:99], v[38:41]
	ds_read_b128 v[88:91], v83 offset:33472
	ds_read_b128 v[92:95], v101 offset:384
	ds_read_b128 v[96:99], v101 offset:448
	s_waitcnt lgkmcnt(0)
	v_mfma_f32_16x16x32_bf16 v[42:45], v[84:87], v[92:95], v[42:45]
	ds_read_b128 v[84:87], v83 offset:33536
	v_mfma_f32_16x16x32_bf16 v[46:49], v[88:91], v[96:99], v[46:49]
	ds_read_b128 v[88:91], v83 offset:33600
	ds_read_b128 v[92:95], v101 offset:512
	ds_read_b128 v[96:99], v101 offset:576
	s_waitcnt lgkmcnt(0)
	v_mfma_f32_16x16x32_bf16 v[34:37], v[84:87], v[92:95], v[34:37]
	ds_read_b128 v[84:87], v83 offset:33664
	v_mfma_f32_16x16x32_bf16 v[38:41], v[88:91], v[96:99], v[38:41]
	ds_read_b128 v[88:91], v83 offset:33728
	ds_read_b128 v[92:95], v101 offset:640
	ds_read_b128 v[96:99], v101 offset:704
	s_waitcnt lgkmcnt(0)
	v_mfma_f32_16x16x32_bf16 v[42:45], v[84:87], v[92:95], v[42:45]
	ds_read_b128 v[84:87], v83 offset:33792
	ds_read_b128 v[92:95], v83 offset:33856
	v_mfma_f32_16x16x32_bf16 v[46:49], v[88:91], v[96:99], v[46:49]
	ds_read_b128 v[88:91], v101 offset:768
	ds_read_b128 v[96:99], v101 offset:832
	s_waitcnt lgkmcnt(0)
	v_mfma_f32_16x16x32_bf16 v[34:37], v[84:87], v[88:91], v[34:37]
	ds_read_b128 v[84:87], v83 offset:33920
	ds_read_b128 v[88:91], v83 offset:33984
	v_mfma_f32_16x16x32_bf16 v[38:41], v[92:95], v[96:99], v[38:41]
	ds_read_b128 v[92:95], v101 offset:896
	ds_read_b128 v[96:99], v101 offset:960
	s_waitcnt lgkmcnt(0)
	v_mfma_f32_16x16x32_bf16 v[42:45], v[84:87], v[92:95], v[42:45]
	ds_read_b128 v[84:87], v83 offset:34048
	ds_read_b128 v[92:95], v83 offset:34112
	v_mfma_f32_16x16x32_bf16 v[46:49], v[88:91], v[96:99], v[46:49]
	ds_read_b128 v[88:91], v101 offset:1024
	ds_read_b128 v[96:99], v101 offset:1088
	s_waitcnt lgkmcnt(0)
	v_mfma_f32_16x16x32_bf16 v[34:37], v[84:87], v[88:91], v[34:37]
	ds_read_b128 v[84:87], v83 offset:34176
	ds_read_b128 v[88:91], v83 offset:34240
	v_mfma_f32_16x16x32_bf16 v[38:41], v[92:95], v[96:99], v[38:41]
	ds_read_b128 v[92:95], v101 offset:1152
	ds_read_b128 v[96:99], v101 offset:1216
	s_waitcnt lgkmcnt(0)
	v_mfma_f32_16x16x32_bf16 v[42:45], v[84:87], v[92:95], v[42:45]
	ds_read_b128 v[84:87], v83 offset:34304
	ds_read_b128 v[92:95], v83 offset:34368
	v_mfma_f32_16x16x32_bf16 v[46:49], v[88:91], v[96:99], v[46:49]
	ds_read_b128 v[88:91], v101 offset:1280
	ds_read_b128 v[96:99], v101 offset:1344
	s_waitcnt lgkmcnt(0)
	v_mfma_f32_16x16x32_bf16 v[34:37], v[84:87], v[88:91], v[34:37]
	ds_read_b128 v[84:87], v83 offset:34432
	ds_read_b128 v[88:91], v83 offset:34496
	v_mfma_f32_16x16x32_bf16 v[38:41], v[92:95], v[96:99], v[38:41]
	ds_read_b128 v[92:95], v101 offset:1408
	ds_read_b128 v[96:99], v101 offset:1472
	s_waitcnt lgkmcnt(0)
	v_mfma_f32_16x16x32_bf16 v[42:45], v[84:87], v[92:95], v[42:45]
	ds_read_b128 v[84:87], v83 offset:34560
	ds_read_b128 v[92:95], v83 offset:34624
	v_mfma_f32_16x16x32_bf16 v[46:49], v[88:91], v[96:99], v[46:49]
	ds_read_b128 v[88:91], v101 offset:1536
	ds_read_b128 v[96:99], v101 offset:1600
	s_waitcnt lgkmcnt(0)
	v_mfma_f32_16x16x32_bf16 v[34:37], v[84:87], v[88:91], v[34:37]
	ds_read_b128 v[84:87], v83 offset:34688
	ds_read_b128 v[88:91], v83 offset:34752
	v_mfma_f32_16x16x32_bf16 v[38:41], v[92:95], v[96:99], v[38:41]
	ds_read_b128 v[92:95], v101 offset:1664
	ds_read_b128 v[96:99], v101 offset:1728
	s_waitcnt lgkmcnt(0)
	v_mfma_f32_16x16x32_bf16 v[42:45], v[84:87], v[92:95], v[42:45]
	ds_read_b128 v[84:87], v83 offset:34816
	ds_read_b128 v[92:95], v83 offset:34880
	v_mfma_f32_16x16x32_bf16 v[46:49], v[88:91], v[96:99], v[46:49]
	ds_read_b128 v[88:91], v101 offset:1792
	ds_read_b128 v[96:99], v101 offset:1856
	s_waitcnt lgkmcnt(0)
	v_mfma_f32_16x16x32_bf16 v[34:37], v[84:87], v[88:91], v[34:37]
	ds_read_b128 v[84:87], v83 offset:34944
	ds_read_b128 v[88:91], v83 offset:35008
	v_mfma_f32_16x16x32_bf16 v[38:41], v[92:95], v[96:99], v[38:41]
	ds_read_b128 v[92:95], v101 offset:1920
	ds_read_b128 v[96:99], v101 offset:1984
	v_ashrrev_i32_e32 v101, 31, v100
	s_waitcnt lgkmcnt(0)
	v_mfma_f32_16x16x32_bf16 v[42:45], v[84:87], v[92:95], v[42:45]
	s_nop 2
	v_add_f32_e64 v34, v34, v38
	v_add_f32_e64 v35, v35, v39
	v_mfma_f32_16x16x32_bf16 v[46:49], v[88:91], v[96:99], v[46:49]
	s_nop 7
	v_pk_add_f32 v[38:39], v[42:43], v[46:47]
	s_nop 0
	v_pk_add_f32 v[38:39], v[34:35], v[38:39]
	s_nop 1
	v_mov_b32_dpp v34, v38 quad_perm:[1,0,3,2] row_mask:0xf bank_mask:0xf bound_ctrl:1
	v_max_f32_e32 v34, v34, v34
	v_max_f32_e32 v34, v38, v34
	s_nop 1
	v_mov_b32_dpp v35, v34 quad_perm:[2,3,0,1] row_mask:0xf bank_mask:0xf bound_ctrl:1
	v_max_f32_e32 v35, v35, v35
	v_max_f32_e32 v34, v34, v35
	s_nop 1
	v_mov_b32_dpp v35, v34 row_half_mirror row_mask:0xf bank_mask:0xf bound_ctrl:1
	v_max_f32_e32 v35, v35, v35
	v_max_f32_e32 v34, v34, v35
	s_nop 1
	v_mov_b32_dpp v35, v34 row_mirror row_mask:0xf bank_mask:0xf bound_ctrl:1
	v_max_f32_e32 v35, v35, v35
	v_max_f32_e32 v34, v34, v35
	v_sub_f32_e32 v34, v38, v34
	v_mul_f32_e32 v34, 0x3fb8aa3b, v34
	v_exp_f32_e32 v38, v34
	v_lshlrev_b64 v[34:35], 13, v[100:101]
	v_lshl_add_u64 v[34:35], s[26:27], 0, v[34:35]
	v_add_f32_dpp v42, v38, v38 quad_perm:[1,0,3,2] row_mask:0xf bank_mask:0xf bound_ctrl:1
	s_nop 1
	v_add_f32_dpp v42, v42, v42 quad_perm:[2,3,0,1] row_mask:0xf bank_mask:0xf bound_ctrl:1
	s_nop 1
	v_add_f32_dpp v42, v42, v42 row_half_mirror row_mask:0xf bank_mask:0xf bound_ctrl:1
	s_nop 1
	v_mov_b32_dpp v43, v42 row_mirror row_mask:0xf bank_mask:0xf bound_ctrl:1
	s_and_saveexec_b64 s[30:31], vcc
	s_cbranch_execz .LBB0_461
	v_add_f32_e32 v42, v42, v43
	v_rcp_f32_e32 v42, v42
	s_sub_i32 s19, s18, 24
	s_ashr_i32 s0, s19, 11
	s_ashr_i32 s1, s0, 31
	s_and_b32 s19, s19, 0x7ff
	s_lshl_b64 s[0:1], s[0:1], 17
	v_mul_f32_e32 v38, v38, v42
	v_lshl_add_u64 v[42:43], v[34:35], 0, s[0:1]
	s_lshl_b32 s20, s19, 2
	v_lshl_add_u64 v[42:43], v[42:43], 0, s[20:21]
	global_store_dword v[42:43], v38, off
.LBB0_461:
	s_or_b64 exec, exec, s[30:31]
	v_mov_b32_dpp v38, v39 quad_perm:[1,0,3,2] row_mask:0xf bank_mask:0xf bound_ctrl:1
	v_max_f32_e32 v38, v38, v38
	v_max_f32_e32 v42, v39, v39
	v_max_f32_e32 v38, v42, v38
	v_pk_add_f32 v[36:37], v[36:37], v[40:41]
	v_pk_add_f32 v[40:41], v[44:45], v[48:49]
	v_mov_b32_dpp v42, v38 quad_perm:[2,3,0,1] row_mask:0xf bank_mask:0xf bound_ctrl:1
	v_max_f32_e32 v42, v42, v42
	v_max_f32_e32 v38, v38, v42
	v_pk_add_f32 v[36:37], v[36:37], v[40:41]
	s_nop 0
	v_mov_b32_dpp v42, v38 row_half_mirror row_mask:0xf bank_mask:0xf bound_ctrl:1
	v_max_f32_e32 v42, v42, v42
	v_max_f32_e32 v38, v38, v42
	s_nop 1
	v_mov_b32_dpp v42, v38 row_mirror row_mask:0xf bank_mask:0xf bound_ctrl:1
	v_max_f32_e32 v42, v42, v42
	v_max_f32_e32 v38, v38, v42
	v_sub_f32_e32 v38, v39, v38
	v_mul_f32_e32 v38, 0x3fb8aa3b, v38
	v_exp_f32_e32 v38, v38
	s_nop 1
	v_add_f32_dpp v39, v38, v38 quad_perm:[1,0,3,2] row_mask:0xf bank_mask:0xf bound_ctrl:1
	s_nop 1
	v_add_f32_dpp v39, v39, v39 quad_perm:[2,3,0,1] row_mask:0xf bank_mask:0xf bound_ctrl:1
	s_nop 1
	v_add_f32_dpp v39, v39, v39 row_half_mirror row_mask:0xf bank_mask:0xf bound_ctrl:1
	s_nop 1
	v_mov_b32_dpp v40, v39 row_mirror row_mask:0xf bank_mask:0xf bound_ctrl:1
	s_and_saveexec_b64 s[30:31], vcc
	s_cbranch_execz .LBB0_463
	v_add_f32_e32 v39, v39, v40
	v_rcp_f32_e32 v39, v39
	s_add_i32 s19, s18, -16
	s_ashr_i32 s0, s19, 11
	s_ashr_i32 s1, s0, 31
	s_and_b32 s19, s19, 0x7ff
	s_lshl_b64 s[0:1], s[0:1], 17
	v_mul_f32_e32 v40, v38, v39
	v_lshl_add_u64 v[38:39], v[34:35], 0, s[0:1]
	s_lshl_b32 s20, s19, 2
	v_lshl_add_u64 v[38:39], v[38:39], 0, s[20:21]
	global_store_dword v[38:39], v40, off
.LBB0_463:
	s_or_b64 exec, exec, s[30:31]
	v_mov_b32_dpp v38, v36 quad_perm:[1,0,3,2] row_mask:0xf bank_mask:0xf bound_ctrl:1
	v_max_f32_e32 v38, v38, v38
	v_max_f32_e32 v39, v36, v36
	v_max_f32_e32 v38, v39, v38
	s_nop 1
	v_mov_b32_dpp v39, v38 quad_perm:[2,3,0,1] row_mask:0xf bank_mask:0xf bound_ctrl:1
	v_max_f32_e32 v39, v39, v39
	v_max_f32_e32 v38, v38, v39
	s_nop 1
	v_mov_b32_dpp v39, v38 row_half_mirror row_mask:0xf bank_mask:0xf bound_ctrl:1
	v_max_f32_e32 v39, v39, v39
	v_max_f32_e32 v38, v38, v39
	s_nop 1
	v_mov_b32_dpp v39, v38 row_mirror row_mask:0xf bank_mask:0xf bound_ctrl:1
	v_max_f32_e32 v39, v39, v39
	v_max_f32_e32 v38, v38, v39
	v_sub_f32_e32 v36, v36, v38
	v_mul_f32_e32 v36, 0x3fb8aa3b, v36
	v_exp_f32_e32 v36, v36
	s_nop 1
	v_add_f32_dpp v38, v36, v36 quad_perm:[1,0,3,2] row_mask:0xf bank_mask:0xf bound_ctrl:1
	s_nop 1
	v_add_f32_dpp v38, v38, v38 quad_perm:[2,3,0,1] row_mask:0xf bank_mask:0xf bound_ctrl:1
	s_nop 1
	v_add_f32_dpp v38, v38, v38 row_half_mirror row_mask:0xf bank_mask:0xf bound_ctrl:1
	s_nop 1
	v_mov_b32_dpp v39, v38 row_mirror row_mask:0xf bank_mask:0xf bound_ctrl:1
	s_and_saveexec_b64 s[30:31], vcc
	s_cbranch_execz .LBB0_465
	v_add_f32_e32 v38, v38, v39
	v_rcp_f32_e32 v38, v38
	s_add_i32 s19, s18, -8
	s_ashr_i32 s0, s19, 11
	s_ashr_i32 s1, s0, 31
	s_and_b32 s19, s19, 0x7ff
	s_lshl_b64 s[0:1], s[0:1], 17
	v_mul_f32_e32 v36, v36, v38
	v_lshl_add_u64 v[38:39], v[34:35], 0, s[0:1]
	s_lshl_b32 s20, s19, 2
	v_lshl_add_u64 v[38:39], v[38:39], 0, s[20:21]
	global_store_dword v[38:39], v36, off
.LBB0_465:
	s_or_b64 exec, exec, s[30:31]
	v_mov_b32_dpp v36, v37 quad_perm:[1,0,3,2] row_mask:0xf bank_mask:0xf bound_ctrl:1
	v_max_f32_e32 v36, v36, v36
	v_max_f32_e32 v38, v37, v37
	v_max_f32_e32 v36, v38, v36
	s_nop 1
	v_mov_b32_dpp v38, v36 quad_perm:[2,3,0,1] row_mask:0xf bank_mask:0xf bound_ctrl:1
	v_max_f32_e32 v38, v38, v38
	v_max_f32_e32 v36, v36, v38
	s_nop 1
	v_mov_b32_dpp v38, v36 row_half_mirror row_mask:0xf bank_mask:0xf bound_ctrl:1
	v_max_f32_e32 v38, v38, v38
	v_max_f32_e32 v36, v36, v38
	s_nop 1
	v_mov_b32_dpp v38, v36 row_mirror row_mask:0xf bank_mask:0xf bound_ctrl:1
	v_max_f32_e32 v38, v38, v38
	v_max_f32_e32 v36, v36, v38
	v_sub_f32_e32 v36, v37, v36
	v_mul_f32_e32 v36, 0x3fb8aa3b, v36
	v_exp_f32_e32 v36, v36
	s_nop 1
	v_add_f32_dpp v37, v36, v36 quad_perm:[1,0,3,2] row_mask:0xf bank_mask:0xf bound_ctrl:1
	s_nop 1
	v_add_f32_dpp v37, v37, v37 quad_perm:[2,3,0,1] row_mask:0xf bank_mask:0xf bound_ctrl:1
	s_nop 1
	v_add_f32_dpp v37, v37, v37 row_half_mirror row_mask:0xf bank_mask:0xf bound_ctrl:1
	s_nop 1
	v_mov_b32_dpp v38, v37 row_mirror row_mask:0xf bank_mask:0xf bound_ctrl:1
	s_and_saveexec_b64 s[30:31], vcc
	s_cbranch_execz .LBB0_456
	v_add_f32_e32 v37, v37, v38
	v_rcp_f32_e32 v37, v37
	s_ashr_i32 s0, s18, 11
	s_ashr_i32 s1, s0, 31
	s_and_b32 s18, s18, 0x7ff
	s_lshl_b64 s[0:1], s[0:1], 17
	v_lshl_add_u64 v[34:35], v[34:35], 0, s[0:1]
	s_lshl_b32 s20, s18, 2
	v_mul_f32_e32 v36, v36, v37
	v_lshl_add_u64 v[34:35], v[34:35], 0, s[20:21]
	global_store_dword v[34:35], v36, off
	s_branch .LBB0_456

.LBB0_1068:
	s_or_b64 exec, exec, s[20:21]
	s_lshl_b32 s0, s7, 8
	s_add_i32 s0, s0, s97
	s_ashr_i32 s1, s0, 31
	s_lshl_b64 s[10:11], s[0:1], 11
	v_lshl_add_u64 v[38:39], v[54:55], 0, s[10:11]
	s_mov_b64 s[10:11], 0x4000
	v_add_co_u32_e32 v44, vcc, 0x4000, v38
	s_waitcnt lgkmcnt(0)
	s_barrier
	global_load_dwordx4 v[2:5], v[50:51], off
	global_load_dwordx4 v[6:9], v[50:51], off offset:1024
	global_load_dwordx4 v[10:13], v[52:53], off
	global_load_dwordx4 v[14:17], v[52:53], off offset:1024
	global_load_dwordx4 v[18:21], v[50:51], off offset:2048
	global_load_dwordx4 v[22:25], v[50:51], off offset:3072
	global_load_dwordx4 v[26:29], v[52:53], off offset:2048
	global_load_dwordx4 v[30:33], v[52:53], off offset:3072
	v_lshl_add_u64 v[42:43], v[38:39], 0, s[10:11]
	v_addc_co_u32_e32 v45, vcc, 0, v39, vcc
	global_load_dwordx2 v[36:37], v[38:39], off
	global_load_dwordx2 v[34:35], v[38:39], off offset:512
	global_load_dwordx2 v[40:41], v[38:39], off offset:1024
	s_nop 0
	global_load_dwordx2 v[38:39], v[38:39], off offset:1536
	s_nop 0
	global_load_dwordx2 v[60:61], v[44:45], off
	global_load_dwordx2 v[62:63], v[42:43], off offset:512
	global_load_dwordx2 v[64:65], v[42:43], off offset:1024
	global_load_dwordx2 v[66:67], v[42:43], off offset:1536
	s_mov_b32 s10, 0
	s_add_i32 s11, s0, 16
	s_mov_b32 s24, 0
	s_waitcnt vmcnt(0)
	v_mov_b64_e32 v[224:225], v[60:61]
	v_mov_b64_e32 v[226:227], v[62:63]
	v_mov_b64_e32 v[228:229], v[64:65]
	v_mov_b64_e32 v[230:231], v[66:67]
	s_branch .LBB0_1071

.LBB0_1070:
	s_add_i32 s24, s24, 1
	s_add_i32 s10, s10, 8
	s_cmpk_lg_i32 s10, 0x100
	v_mov_b64_e32 v[38:39], v[66:67]
	v_mov_b64_e32 v[40:41], v[64:65]
	v_mov_b64_e32 v[34:35], v[62:63]
	v_mov_b64_e32 v[36:37], v[60:61]
	s_waitcnt lgkmcnt(0)
	s_cbranch_scc0 .LBB0_1054
.LBB0_1071:
	s_waitcnt lgkmcnt(0)
	v_lshlrev_b32_e32 v77, 16, v37
	v_lshlrev_b32_e32 v76, 16, v36
	v_and_b32_e32 v37, 0xffff0000, v37
	v_and_b32_e32 v36, 0xffff0000, v36
	v_pk_add_f32 v[68:69], v[76:77], v[36:37]
	v_lshlrev_b32_e32 v87, 16, v35
	v_lshlrev_b32_e32 v86, 16, v34
	v_and_b32_e32 v35, 0xffff0000, v35
	v_and_b32_e32 v34, 0xffff0000, v34
	v_lshlrev_b32_e32 v46, 16, v39
	v_and_b32_e32 v48, 0xffff0000, v39
	v_add_f32_e32 v39, v68, v69
	v_pk_add_f32 v[68:69], v[86:87], v[34:35]
	v_lshlrev_b32_e32 v42, 16, v40
	v_and_b32_e32 v43, 0xffff0000, v40
	v_lshlrev_b32_e32 v40, 16, v41
	v_and_b32_e32 v41, 0xffff0000, v41
	v_pk_add_f32 v[68:69], v[68:69], v[68:69] op_sel_hi:[0,1]
	v_lshlrev_b32_e32 v44, 16, v38
	v_and_b32_e32 v38, 0xffff0000, v38
	v_add_f32_e32 v49, 0, v39
	v_add_f32_e32 v45, v42, v43
	v_add_f32_e32 v39, v40, v41
	v_mov_b32_e32 v47, v69
	v_pk_add_f32 v[70:71], v[44:45], v[38:39]
	v_pk_add_f32 v[68:69], v[46:47], v[48:49]
	s_min_u32 s0, s24, 29
	v_pk_add_f32 v[68:69], v[70:71], v[68:69]
	s_lshl_b32 s0, s0, 3
	v_add_f32_e32 v39, v68, v69
	s_add_i32 s20, s11, s0
	s_nop 0
	v_add_f32_dpp v39, v39, v39 quad_perm:[1,0,3,2] row_mask:0xf bank_mask:0xf bound_ctrl:1
	s_nop 1
	v_add_f32_dpp v39, v39, v39 quad_perm:[2,3,0,1] row_mask:0xf bank_mask:0xf bound_ctrl:1
	s_nop 1
	v_add_f32_dpp v39, v39, v39 row_half_mirror row_mask:0xf bank_mask:0xf bound_ctrl:1
	s_nop 1
	v_add_f32_dpp v39, v39, v39 row_mirror row_mask:0xf bank_mask:0xf bound_ctrl:1
	s_nop 0
	v_readlane_b32 s21, v39, 16
	v_readlane_b32 s22, v39, 48
	v_readlane_b32 s0, v39, 0
	v_readlane_b32 s1, v39, 32
	v_mov_b32_e32 v68, s21
	v_mov_b32_e32 v69, s22
	v_pk_add_f32 v[68:69], s[0:1], v[68:69]
	s_nop 0
	v_add_f32_e32 v39, v68, v69
	v_fmac_f32_e32 v36, 0xba800000, v39
	v_fmac_f32_e32 v37, 0xba800000, v39
	v_fmac_f32_e32 v77, 0xba800000, v39
	v_fmac_f32_e32 v76, 0xba800000, v39
	v_mov_b32_e32 v88, v77
	v_mov_b32_e32 v89, v37
	v_mov_b32_e32 v77, v36
	v_fmac_f32_e32 v34, 0xba800000, v39
	v_fmac_f32_e32 v35, 0xba800000, v39
	v_fmac_f32_e32 v87, 0xba800000, v39
	v_pk_mul_f32 v[68:69], v[88:89], v[88:89]
	v_pk_mul_f32 v[36:37], v[76:77], v[76:77]
	v_fmac_f32_e32 v86, 0xba800000, v39
	v_mov_b32_e32 v90, v87
	v_mov_b32_e32 v91, v35
	v_mov_b32_e32 v87, v34
	v_pk_mov_b32 v[70:71], v[36:37], v[68:69] op_sel:[1,0]
	v_mov_b32_e32 v37, v69
	v_pk_mul_f32 v[68:69], v[90:91], v[90:91]
	v_pk_mul_f32 v[34:35], v[86:87], v[86:87]
	v_pk_add_f32 v[36:37], v[70:71], v[36:37]
	v_pk_mov_b32 v[70:71], v[34:35], v[68:69] op_sel:[1,0]
	v_mov_b32_e32 v35, v69
	v_pk_add_f32 v[34:35], v[70:71], v[34:35]
	v_fmac_f32_e32 v42, 0xba800000, v39
	v_pk_add_f32 v[34:35], v[34:35], v[34:35] op_sel_hi:[0,1]
	v_fmac_f32_e32 v43, 0xba800000, v39
	v_fmac_f32_e32 v40, 0xba800000, v39
	v_mul_f32_e32 v34, v42, v42
	v_fmac_f32_e32 v41, 0xba800000, v39
	v_pk_fma_f32 v[68:69], v[42:43], v[42:43], v[34:35] op_sel_hi:[1,1,0]
	v_mul_f32_e32 v34, v40, v40
	v_pk_add_f32 v[36:37], v[36:37], v[36:37] op_sel_hi:[0,1]
	v_pk_fma_f32 v[70:71], v[40:41], v[40:41], v[34:35] op_sel_hi:[1,1,0]
	v_fmac_f32_e32 v48, 0xba800000, v39
	v_fmac_f32_e32 v46, 0xba800000, v39
	v_fmac_f32_e32 v38, 0xba800000, v39
	v_fmac_f32_e32 v44, 0xba800000, v39
	v_mul_f32_e32 v68, v44, v44
	v_mul_f32_e32 v70, v38, v38
	v_mul_f32_e32 v36, v46, v46
	v_mul_f32_e32 v34, v48, v48
	v_pk_add_f32 v[68:69], v[68:69], v[70:71]
	v_pk_add_f32 v[34:35], v[36:37], v[34:35]
	v_mov_b32_e32 v47, v48
	v_pk_add_f32 v[34:35], v[68:69], v[34:35]
	s_nop 0
	v_add_f32_e32 v34, v34, v35
	s_nop 1
	v_add_f32_dpp v34, v34, v34 quad_perm:[1,0,3,2] row_mask:0xf bank_mask:0xf bound_ctrl:1
	s_nop 1
	v_add_f32_dpp v34, v34, v34 quad_perm:[2,3,0,1] row_mask:0xf bank_mask:0xf bound_ctrl:1
	s_nop 1
	v_add_f32_dpp v34, v34, v34 row_half_mirror row_mask:0xf bank_mask:0xf bound_ctrl:1
	s_nop 1
	v_add_f32_dpp v34, v34, v34 row_mirror row_mask:0xf bank_mask:0xf bound_ctrl:1
	s_nop 0
	v_readlane_b32 s21, v34, 16
	v_readlane_b32 s22, v34, 48
	v_readlane_b32 s0, v34, 0
	v_readlane_b32 s1, v34, 32
	v_mov_b32_e32 v34, s21
	v_mov_b32_e32 v35, s22
	v_pk_add_f32 v[34:35], s[0:1], v[34:35]
	s_mov_b32 s0, 0xf800000
	v_add_f32_e32 v34, v34, v35
	v_fmamk_f32 v34, v34, 0x3a800000, v82
	s_ashr_i32 s21, s20, 31
	v_mul_f32_e32 v35, 0x4f800000, v34
	v_cmp_gt_f32_e32 vcc, s0, v34
	s_lshl_b64 s[0:1], s[20:21], 11
	s_and_b32 s22, s24, 3
	v_cndmask_b32_e32 v36, v34, v35, vcc
	v_lshl_add_u64 v[34:35], v[54:55], 0, s[0:1]
	s_waitcnt vmcnt(8)
	v_mov_b64_e32 v[66:67], v[230:231]
	v_mov_b64_e32 v[64:65], v[228:229]
	v_mov_b64_e32 v[62:63], v[226:227]
	v_mov_b64_e32 v[60:61], v[224:225]
	global_load_dwordx2 v[224:225], v[34:35], off
	global_load_dwordx2 v[226:227], v[34:35], off offset:512
	global_load_dwordx2 v[228:229], v[34:35], off offset:1024
	global_load_dwordx2 v[230:231], v[34:35], off offset:1536
	v_sqrt_f32_e32 v37, v36
	s_mul_i32 s23, s22, 0x810
	s_add_i32 s23, s87, s23
	v_add_u32_e32 v39, -1, v37
	v_fma_f32 v45, -v39, v37, v36
	v_cmp_ge_f32_e64 s[20:21], 0, v45
	v_add_u32_e32 v45, 1, v37
	s_nop 0
	v_cndmask_b32_e64 v39, v37, v39, s[20:21]
	v_fma_f32 v37, -v45, v37, v36
	v_cmp_lt_f32_e64 s[20:21], 0, v37
	s_nop 1
	v_cndmask_b32_e64 v37, v39, v45, s[20:21]
	v_mul_f32_e32 v39, 0x37800000, v37
	v_cndmask_b32_e32 v37, v37, v39, vcc
	v_cmp_class_f32_e32 vcc, v36, v83
	s_add_i32 s20, s4, s10
	s_ashr_i32 s21, s20, 31
	v_cndmask_b32_e32 v36, v37, v36, vcc
	v_div_scale_f32 v37, s[0:1], v36, v36, 1.0
	v_rcp_f32_e32 v39, v37
	s_lshl_b64 s[0:1], s[20:21], 11
	v_fma_f32 v34, -v37, v39, 1.0
	v_fmac_f32_e32 v39, v34, v39
	v_div_scale_f32 v34, vcc, 1.0, v36, 1.0
	v_mul_f32_e32 v35, v34, v39
	v_fma_f32 v45, -v37, v35, v34
	v_fmac_f32_e32 v35, v45, v39
	v_fma_f32 v34, -v37, v35, v34
	v_div_fmas_f32 v34, v34, v39, v35
	v_div_fixup_f32 v34, v34, v36, 1.0
	v_mov_b32_e32 v45, v38
	v_pk_mul_f32 v[36:37], v[76:77], v[34:35] op_sel_hi:[1,0]
	v_pk_mul_f32 v[76:77], v[88:89], v[34:35] op_sel_hi:[1,0]
	v_pk_mul_f32 v[38:39], v[44:45], v[34:35] op_sel_hi:[1,0]
	v_mov_b32_e32 v44, v168
	v_pk_fma_f32 v[76:77], v[4:5], v[76:77], v[12:13]
	v_pk_fma_f32 v[36:37], v[2:3], v[36:37], v[10:11]
	v_pk_mul_f32 v[86:87], v[86:87], v[34:35] op_sel_hi:[1,0]
	v_pk_mul_f32 v[88:89], v[90:91], v[34:35] op_sel_hi:[1,0]
	v_pk_fma_f32 v[86:87], v[6:7], v[86:87], v[14:15]
	v_pk_fma_f32 v[88:89], v[8:9], v[88:89], v[16:17]
	v_pk_mul_f32 v[42:43], v[42:43], v[34:35] op_sel_hi:[1,0]
	v_pk_mul_f32 v[40:41], v[40:41], v[34:35] op_sel_hi:[1,0]
	v_pk_mul_f32 v[34:35], v[46:47], v[34:35] op_sel_hi:[1,0]
	v_lshl_add_u32 v48, v44, 3, s23
	v_cvt_pk_bf16_f32 v44, v36, v37
	v_cvt_pk_bf16_f32 v45, v76, v77
	v_lshl_add_u64 v[46:47], v[56:57], 0, s[0:1]
	v_pk_fma_f32 v[40:41], v[20:21], v[40:41], v[28:29]
	v_pk_fma_f32 v[42:43], v[18:19], v[42:43], v[26:27]
	global_store_dwordx2 v[46:47], v[44:45], off
	ds_write_b64 v48, v[44:45] offset:33024
	v_cvt_pk_bf16_f32 v44, v86, v87
	v_cvt_pk_bf16_f32 v45, v88, v89
	v_pk_fma_f32 v[34:35], v[24:25], v[34:35], v[32:33]
	v_pk_fma_f32 v[38:39], v[22:23], v[38:39], v[30:31]
	global_store_dwordx2 v[46:47], v[44:45], off offset:512
	ds_write_b64 v48, v[44:45] offset:33536
	v_cvt_pk_bf16_f32 v44, v42, v43
	v_cvt_pk_bf16_f32 v45, v40, v41
	global_store_dwordx2 v[46:47], v[44:45], off offset:1024
	ds_write_b64 v48, v[44:45] offset:34048
	v_cvt_pk_bf16_f32 v44, v38, v39
	v_cvt_pk_bf16_f32 v45, v34, v35
	global_store_dwordx2 v[46:47], v[44:45], off offset:1536
	ds_write_b64 v48, v[44:45] offset:34560
	v_med3_f32 v36, v36, s6, v84
	v_med3_f32 v37, v37, s6, v84
	v_mov_b32_e32 v44, 0
	v_cvt_pk_fp8_f32 v44, v36, v37
	v_med3_f32 v36, v76, s6, v84
	v_med3_f32 v37, v77, s6, v84
	v_med3_f32 v45, v86, s6, v84
	v_cvt_pk_fp8_f32 v44, v36, v37 op_sel:[0,0,1]
	v_med3_f32 v46, v87, s6, v84
	v_mov_b32_e32 v47, 0
	v_cvt_pk_fp8_f32 v47, v45, v46
	s_lshl_b64 s[0:1], s[20:21], 10
	v_lshl_add_u64 v[36:37], v[58:59], 0, s[0:1]
	global_store_dword v[36:37], v44, off
	v_med3_f32 v44, v88, s6, v84
	v_med3_f32 v45, v89, s6, v84
	v_cvt_pk_fp8_f32 v47, v44, v45 op_sel:[0,0,1]
	v_med3_f32 v42, v42, s6, v84
	v_med3_f32 v43, v43, s6, v84
	v_mov_b32_e32 v44, 0
	v_cvt_pk_fp8_f32 v44, v42, v43
	v_med3_f32 v38, v38, s6, v84
	v_med3_f32 v39, v39, s6, v84
	v_mov_b32_e32 v42, 0
	v_cvt_pk_fp8_f32 v42, v38, v39
	v_med3_f32 v34, v34, s6, v84
	v_med3_f32 v35, v35, s6, v84
	v_med3_f32 v40, v40, s6, v84
	v_med3_f32 v41, v41, s6, v84
	v_cvt_pk_fp8_f32 v42, v34, v35 op_sel:[0,0,1]
	v_cvt_pk_fp8_f32 v44, v40, v41 op_sel:[0,0,1]
	s_cmp_lg_u32 s22, 3
	global_store_dword v[36:37], v47, off offset:256
	global_store_dword v[36:37], v44, off offset:512
	global_store_dword v[36:37], v42, off offset:768
	s_cbranch_scc1 .LBB0_1070
	v_mov_b32_e32 v76, v168
	s_nop 0
	v_and_b32_e32 v34, 3, v76
	v_mul_u32_u24_e32 v34, 0x810, v34
	v_and_b32_e32 v35, -16, v76
	v_add3_u32 v77, s87, v34, v35
	v_and_b32_e32 v34, 15, v76
	v_mul_u32_u24_e32 v34, 0x810, v34
	v_add3_u32 v85, 0, v34, v35
	ds_read_b128 v[34:37], v77 offset:33024
	ds_read_b128 v[38:41], v85
	s_waitcnt lgkmcnt(0)
	v_mfma_f32_16x16x32_bf16 v[34:37], v[34:37], v[38:41], 0
	ds_read_b128 v[38:41], v77 offset:33088
	ds_read_b128 v[42:45], v85 offset:64
	v_cmp_gt_i32_e32 vcc, 16, v76
	s_waitcnt lgkmcnt(0)
	v_mfma_f32_16x16x32_bf16 v[38:41], v[38:41], v[42:45], 0
	ds_read_b128 v[42:45], v77 offset:33152
	ds_read_b128 v[46:49], v85 offset:128
	s_waitcnt lgkmcnt(0)
	v_mfma_f32_16x16x32_bf16 v[42:45], v[42:45], v[46:49], 0
	ds_read_b128 v[46:49], v77 offset:33216
	ds_read_b128 v[86:89], v85 offset:192
	s_waitcnt lgkmcnt(0)
	v_mfma_f32_16x16x32_bf16 v[46:49], v[46:49], v[86:89], 0
	ds_read_b128 v[86:89], v77 offset:33280
	ds_read_b128 v[90:93], v85 offset:256
	s_waitcnt lgkmcnt(0)
	v_mfma_f32_16x16x32_bf16 v[34:37], v[86:89], v[90:93], v[34:37]
	ds_read_b128 v[86:89], v77 offset:33344
	ds_read_b128 v[90:93], v85 offset:320
	s_waitcnt lgkmcnt(0)
	v_mfma_f32_16x16x32_bf16 v[38:41], v[86:89], v[90:93], v[38:41]
	ds_read_b128 v[86:89], v77 offset:33408
	ds_read_b128 v[90:93], v85 offset:384
	s_waitcnt lgkmcnt(0)
	v_mfma_f32_16x16x32_bf16 v[42:45], v[86:89], v[90:93], v[42:45]
	ds_read_b128 v[86:89], v77 offset:33472
	ds_read_b128 v[90:93], v85 offset:448
	s_waitcnt lgkmcnt(0)
	v_mfma_f32_16x16x32_bf16 v[46:49], v[86:89], v[90:93], v[46:49]
	ds_read_b128 v[86:89], v77 offset:33536
	ds_read_b128 v[90:93], v85 offset:512
	s_waitcnt lgkmcnt(0)
	v_mfma_f32_16x16x32_bf16 v[34:37], v[86:89], v[90:93], v[34:37]
	ds_read_b128 v[86:89], v77 offset:33600
	ds_read_b128 v[90:93], v85 offset:576
	s_waitcnt lgkmcnt(0)
	v_mfma_f32_16x16x32_bf16 v[38:41], v[86:89], v[90:93], v[38:41]
	ds_read_b128 v[86:89], v77 offset:33664
	ds_read_b128 v[90:93], v85 offset:640
	s_waitcnt lgkmcnt(0)
	v_mfma_f32_16x16x32_bf16 v[42:45], v[86:89], v[90:93], v[42:45]
	ds_read_b128 v[86:89], v77 offset:33728
	ds_read_b128 v[90:93], v85 offset:704
	s_waitcnt lgkmcnt(0)
	v_mfma_f32_16x16x32_bf16 v[46:49], v[86:89], v[90:93], v[46:49]
	ds_read_b128 v[86:89], v77 offset:33792
	ds_read_b128 v[90:93], v85 offset:768
	s_waitcnt lgkmcnt(0)
	v_mfma_f32_16x16x32_bf16 v[34:37], v[86:89], v[90:93], v[34:37]
	ds_read_b128 v[86:89], v77 offset:33856
	ds_read_b128 v[90:93], v85 offset:832
	s_waitcnt lgkmcnt(0)
	v_mfma_f32_16x16x32_bf16 v[38:41], v[86:89], v[90:93], v[38:41]
	ds_read_b128 v[86:89], v77 offset:33920
	ds_read_b128 v[90:93], v85 offset:896
	s_waitcnt lgkmcnt(0)
	v_mfma_f32_16x16x32_bf16 v[42:45], v[86:89], v[90:93], v[42:45]
	ds_read_b128 v[86:89], v77 offset:33984
	ds_read_b128 v[90:93], v85 offset:960
	s_waitcnt lgkmcnt(0)
	v_mfma_f32_16x16x32_bf16 v[46:49], v[86:89], v[90:93], v[46:49]
	ds_read_b128 v[86:89], v77 offset:34048
	ds_read_b128 v[90:93], v85 offset:1024
	s_waitcnt lgkmcnt(0)
	v_mfma_f32_16x16x32_bf16 v[34:37], v[86:89], v[90:93], v[34:37]
	ds_read_b128 v[86:89], v77 offset:34112
	ds_read_b128 v[90:93], v85 offset:1088
	s_waitcnt lgkmcnt(0)
	v_mfma_f32_16x16x32_bf16 v[38:41], v[86:89], v[90:93], v[38:41]
	ds_read_b128 v[86:89], v77 offset:34176
	ds_read_b128 v[90:93], v85 offset:1152
	s_waitcnt lgkmcnt(0)
	v_mfma_f32_16x16x32_bf16 v[42:45], v[86:89], v[90:93], v[42:45]
	ds_read_b128 v[86:89], v77 offset:34240
	ds_read_b128 v[90:93], v85 offset:1216
	s_waitcnt lgkmcnt(0)
	v_mfma_f32_16x16x32_bf16 v[46:49], v[86:89], v[90:93], v[46:49]
	ds_read_b128 v[86:89], v77 offset:34304
	ds_read_b128 v[90:93], v85 offset:1280
	s_waitcnt lgkmcnt(0)
	v_mfma_f32_16x16x32_bf16 v[34:37], v[86:89], v[90:93], v[34:37]
	ds_read_b128 v[86:89], v77 offset:34368
	ds_read_b128 v[90:93], v85 offset:1344
	s_waitcnt lgkmcnt(0)
	v_mfma_f32_16x16x32_bf16 v[38:41], v[86:89], v[90:93], v[38:41]
	ds_read_b128 v[86:89], v77 offset:34432
	ds_read_b128 v[90:93], v85 offset:1408
	s_waitcnt lgkmcnt(0)
	v_mfma_f32_16x16x32_bf16 v[42:45], v[86:89], v[90:93], v[42:45]
	ds_read_b128 v[86:89], v77 offset:34496
	ds_read_b128 v[90:93], v85 offset:1472
	s_waitcnt lgkmcnt(0)
	v_mfma_f32_16x16x32_bf16 v[46:49], v[86:89], v[90:93], v[46:49]
	ds_read_b128 v[86:89], v77 offset:34560
	ds_read_b128 v[90:93], v85 offset:1536
	s_waitcnt lgkmcnt(0)
	v_mfma_f32_16x16x32_bf16 v[34:37], v[86:89], v[90:93], v[34:37]
	ds_read_b128 v[86:89], v77 offset:34624
	ds_read_b128 v[90:93], v85 offset:1600
	s_waitcnt lgkmcnt(0)
	v_mfma_f32_16x16x32_bf16 v[38:41], v[86:89], v[90:93], v[38:41]
	ds_read_b128 v[86:89], v77 offset:34688
	ds_read_b128 v[90:93], v85 offset:1664
	s_waitcnt lgkmcnt(0)
	v_mfma_f32_16x16x32_bf16 v[42:45], v[86:89], v[90:93], v[42:45]
	ds_read_b128 v[86:89], v77 offset:34752
	ds_read_b128 v[90:93], v85 offset:1728
	s_waitcnt lgkmcnt(0)
	v_mfma_f32_16x16x32_bf16 v[46:49], v[86:89], v[90:93], v[46:49]
	ds_read_b128 v[86:89], v77 offset:34816
	ds_read_b128 v[90:93], v85 offset:1792
	s_waitcnt lgkmcnt(0)
	v_mfma_f32_16x16x32_bf16 v[34:37], v[86:89], v[90:93], v[34:37]
	ds_read_b128 v[86:89], v77 offset:34880
	ds_read_b128 v[90:93], v85 offset:1856
	s_waitcnt lgkmcnt(0)
	v_mfma_f32_16x16x32_bf16 v[38:41], v[86:89], v[90:93], v[38:41]
	ds_read_b128 v[86:89], v77 offset:34944
	ds_read_b128 v[90:93], v85 offset:1920
	s_waitcnt lgkmcnt(0)
	v_mfma_f32_16x16x32_bf16 v[42:45], v[86:89], v[90:93], v[42:45]
	ds_read_b128 v[86:89], v77 offset:35008
	ds_read_b128 v[90:93], v85 offset:1984
	s_nop 1
	v_pk_add_f32 v[34:35], v[34:35], v[38:39]
	v_ashrrev_i32_e32 v77, 31, v76
	s_waitcnt lgkmcnt(0)
	v_mfma_f32_16x16x32_bf16 v[46:49], v[86:89], v[90:93], v[46:49]
	s_nop 7
	v_pk_add_f32 v[38:39], v[42:43], v[46:47]
	s_nop 0
	v_pk_add_f32 v[38:39], v[34:35], v[38:39]
	v_lshlrev_b64 v[34:35], 13, v[76:77]
	v_lshl_add_u64 v[34:35], s[30:31], 0, v[34:35]
	v_mov_b32_dpp v42, v38 quad_perm:[1,0,3,2] row_mask:0xf bank_mask:0xf bound_ctrl:1
	v_max_f32_e32 v42, v42, v42
	v_max_f32_e32 v42, v38, v42
	s_nop 1
	v_mov_b32_dpp v43, v42 quad_perm:[2,3,0,1] row_mask:0xf bank_mask:0xf bound_ctrl:1
	v_max_f32_e32 v43, v43, v43
	v_max_f32_e32 v42, v42, v43
	s_nop 1
	v_mov_b32_dpp v43, v42 row_half_mirror row_mask:0xf bank_mask:0xf bound_ctrl:1
	v_max_f32_e32 v43, v43, v43
	v_max_f32_e32 v42, v42, v43
	s_nop 1
	v_mov_b32_dpp v43, v42 row_mirror row_mask:0xf bank_mask:0xf bound_ctrl:1
	v_max_f32_e32 v43, v43, v43
	v_max_f32_e32 v42, v42, v43
	v_sub_f32_e32 v38, v38, v42
	v_mul_f32_e32 v38, 0x3fb8aa3b, v38
	v_exp_f32_e32 v38, v38
	s_nop 1
	v_add_f32_dpp v42, v38, v38 quad_perm:[1,0,3,2] row_mask:0xf bank_mask:0xf bound_ctrl:1
	s_nop 1
	v_add_f32_dpp v42, v42, v42 quad_perm:[2,3,0,1] row_mask:0xf bank_mask:0xf bound_ctrl:1
	s_nop 1
	v_add_f32_dpp v42, v42, v42 row_half_mirror row_mask:0xf bank_mask:0xf bound_ctrl:1
	s_nop 1
	v_mov_b32_dpp v43, v42 row_mirror row_mask:0xf bank_mask:0xf bound_ctrl:1
	s_and_saveexec_b64 s[22:23], vcc
	s_cbranch_execz .LBB0_1074
	v_add_f32_e32 v42, v42, v43
	v_rcp_f32_e32 v42, v42
	s_sub_i32 s21, s20, 24
	s_ashr_i32 s0, s21, 11
	s_ashr_i32 s1, s0, 31
	s_and_b32 s21, s21, 0x7ff
	s_lshl_b64 s[0:1], s[0:1], 17
	v_mul_f32_e32 v38, v38, v42
	v_lshl_add_u64 v[42:43], v[34:35], 0, s[0:1]
	s_lshl_b32 s28, s21, 2
	v_lshl_add_u64 v[42:43], v[42:43], 0, s[28:29]
	global_store_dword v[42:43], v38, off
.LBB0_1074:
	s_or_b64 exec, exec, s[22:23]
	v_mov_b32_dpp v38, v39 quad_perm:[1,0,3,2] row_mask:0xf bank_mask:0xf bound_ctrl:1
	v_max_f32_e32 v38, v38, v38
	v_max_f32_e32 v42, v39, v39
	v_max_f32_e32 v38, v42, v38
	v_pk_add_f32 v[36:37], v[36:37], v[40:41]
	v_pk_add_f32 v[40:41], v[44:45], v[48:49]
	v_mov_b32_dpp v42, v38 quad_perm:[2,3,0,1] row_mask:0xf bank_mask:0xf bound_ctrl:1
	v_max_f32_e32 v42, v42, v42
	v_max_f32_e32 v38, v38, v42
	v_pk_add_f32 v[36:37], v[36:37], v[40:41]
	s_nop 0
	v_mov_b32_dpp v42, v38 row_half_mirror row_mask:0xf bank_mask:0xf bound_ctrl:1
	v_max_f32_e32 v42, v42, v42
	v_max_f32_e32 v38, v38, v42
	s_nop 1
	v_mov_b32_dpp v42, v38 row_mirror row_mask:0xf bank_mask:0xf bound_ctrl:1
	v_max_f32_e32 v42, v42, v42
	v_max_f32_e32 v38, v38, v42
	v_sub_f32_e32 v38, v39, v38
	v_mul_f32_e32 v38, 0x3fb8aa3b, v38
	v_exp_f32_e32 v38, v38
	s_nop 1
	v_add_f32_dpp v39, v38, v38 quad_perm:[1,0,3,2] row_mask:0xf bank_mask:0xf bound_ctrl:1
	s_nop 1
	v_add_f32_dpp v39, v39, v39 quad_perm:[2,3,0,1] row_mask:0xf bank_mask:0xf bound_ctrl:1
	s_nop 1
	v_add_f32_dpp v39, v39, v39 row_half_mirror row_mask:0xf bank_mask:0xf bound_ctrl:1
	s_nop 1
	v_mov_b32_dpp v40, v39 row_mirror row_mask:0xf bank_mask:0xf bound_ctrl:1
	s_and_saveexec_b64 s[22:23], vcc
	s_cbranch_execz .LBB0_1076
	v_add_f32_e32 v39, v39, v40
	v_rcp_f32_e32 v39, v39
	s_add_i32 s21, s20, -16
	s_ashr_i32 s0, s21, 11
	s_ashr_i32 s1, s0, 31
	s_and_b32 s21, s21, 0x7ff
	s_lshl_b64 s[0:1], s[0:1], 17
	v_mul_f32_e32 v40, v38, v39
	v_lshl_add_u64 v[38:39], v[34:35], 0, s[0:1]
	s_lshl_b32 s28, s21, 2
	v_lshl_add_u64 v[38:39], v[38:39], 0, s[28:29]
	global_store_dword v[38:39], v40, off
.LBB0_1076:
	s_or_b64 exec, exec, s[22:23]
	v_mov_b32_dpp v38, v36 quad_perm:[1,0,3,2] row_mask:0xf bank_mask:0xf bound_ctrl:1
	v_max_f32_e32 v38, v38, v38
	v_max_f32_e32 v39, v36, v36
	v_max_f32_e32 v38, v39, v38
	s_nop 1
	v_mov_b32_dpp v39, v38 quad_perm:[2,3,0,1] row_mask:0xf bank_mask:0xf bound_ctrl:1
	v_max_f32_e32 v39, v39, v39
	v_max_f32_e32 v38, v38, v39
	s_nop 1
	v_mov_b32_dpp v39, v38 row_half_mirror row_mask:0xf bank_mask:0xf bound_ctrl:1
	v_max_f32_e32 v39, v39, v39
	v_max_f32_e32 v38, v38, v39
	s_nop 1
	v_mov_b32_dpp v39, v38 row_mirror row_mask:0xf bank_mask:0xf bound_ctrl:1
	v_max_f32_e32 v39, v39, v39
	v_max_f32_e32 v38, v38, v39
	v_sub_f32_e32 v36, v36, v38
	v_mul_f32_e32 v36, 0x3fb8aa3b, v36
	v_exp_f32_e32 v36, v36
	s_nop 1
	v_add_f32_dpp v38, v36, v36 quad_perm:[1,0,3,2] row_mask:0xf bank_mask:0xf bound_ctrl:1
	s_nop 1
	v_add_f32_dpp v38, v38, v38 quad_perm:[2,3,0,1] row_mask:0xf bank_mask:0xf bound_ctrl:1
	s_nop 1
	v_add_f32_dpp v38, v38, v38 row_half_mirror row_mask:0xf bank_mask:0xf bound_ctrl:1
	s_nop 1
	v_mov_b32_dpp v39, v38 row_mirror row_mask:0xf bank_mask:0xf bound_ctrl:1
	s_and_saveexec_b64 s[22:23], vcc
	s_cbranch_execz .LBB0_1078
	v_add_f32_e32 v38, v38, v39
	v_rcp_f32_e32 v38, v38
	s_add_i32 s21, s20, -8
	s_ashr_i32 s0, s21, 11
	s_ashr_i32 s1, s0, 31
	s_and_b32 s21, s21, 0x7ff
	s_lshl_b64 s[0:1], s[0:1], 17
	v_mul_f32_e32 v36, v36, v38
	v_lshl_add_u64 v[38:39], v[34:35], 0, s[0:1]
	s_lshl_b32 s28, s21, 2
	v_lshl_add_u64 v[38:39], v[38:39], 0, s[28:29]
	global_store_dword v[38:39], v36, off
.LBB0_1078:
	s_or_b64 exec, exec, s[22:23]
	v_mov_b32_dpp v36, v37 quad_perm:[1,0,3,2] row_mask:0xf bank_mask:0xf bound_ctrl:1
	v_max_f32_e32 v36, v36, v36
	v_max_f32_e32 v38, v37, v37
	v_max_f32_e32 v36, v38, v36
	s_nop 1
	v_mov_b32_dpp v38, v36 quad_perm:[2,3,0,1] row_mask:0xf bank_mask:0xf bound_ctrl:1
	v_max_f32_e32 v38, v38, v38
	v_max_f32_e32 v36, v36, v38
	s_nop 1
	v_mov_b32_dpp v38, v36 row_half_mirror row_mask:0xf bank_mask:0xf bound_ctrl:1
	v_max_f32_e32 v38, v38, v38
	v_max_f32_e32 v36, v36, v38
	s_nop 1
	v_mov_b32_dpp v38, v36 row_mirror row_mask:0xf bank_mask:0xf bound_ctrl:1
	v_max_f32_e32 v38, v38, v38
	v_max_f32_e32 v36, v36, v38
	v_sub_f32_e32 v36, v37, v36
	v_mul_f32_e32 v36, 0x3fb8aa3b, v36
	v_exp_f32_e32 v36, v36
	s_nop 1
	v_add_f32_dpp v37, v36, v36 quad_perm:[1,0,3,2] row_mask:0xf bank_mask:0xf bound_ctrl:1
	s_nop 1
	v_add_f32_dpp v37, v37, v37 quad_perm:[2,3,0,1] row_mask:0xf bank_mask:0xf bound_ctrl:1
	s_nop 1
	v_add_f32_dpp v37, v37, v37 row_half_mirror row_mask:0xf bank_mask:0xf bound_ctrl:1
	s_nop 1
	v_mov_b32_dpp v38, v37 row_mirror row_mask:0xf bank_mask:0xf bound_ctrl:1
	s_and_saveexec_b64 s[22:23], vcc
	s_cbranch_execz .LBB0_1069
	v_add_f32_e32 v37, v37, v38
	v_rcp_f32_e32 v37, v37
	s_ashr_i32 s0, s20, 11
	s_ashr_i32 s1, s0, 31
	s_and_b32 s20, s20, 0x7ff
	s_lshl_b64 s[0:1], s[0:1], 17
	v_lshl_add_u64 v[34:35], v[34:35], 0, s[0:1]
	s_lshl_b32 s28, s20, 2
	v_mul_f32_e32 v36, v36, v37
	v_lshl_add_u64 v[34:35], v[34:35], 0, s[28:29]
	global_store_dword v[34:35], v36, off
	s_branch .LBB0_1069

.LBB0_1807:
	s_or_b64 exec, exec, s[22:23]
	s_lshl_b32 s0, s7, 8
	s_add_i32 s0, s0, s97
	s_ashr_i32 s1, s0, 31
	s_lshl_b64 s[8:9], s[0:1], 11
	v_lshl_add_u64 v[38:39], v[54:55], 0, s[8:9]
	v_add_co_u32_e32 v44, vcc, 0x4000, v38
	s_waitcnt lgkmcnt(0)
	s_barrier
	global_load_dwordx4 v[2:5], v[50:51], off
	global_load_dwordx4 v[6:9], v[50:51], off offset:1024
	global_load_dwordx4 v[10:13], v[52:53], off
	global_load_dwordx4 v[14:17], v[52:53], off offset:1024
	global_load_dwordx4 v[18:21], v[50:51], off offset:2048
	global_load_dwordx4 v[22:25], v[50:51], off offset:3072
	global_load_dwordx4 v[26:29], v[52:53], off offset:2048
	global_load_dwordx4 v[30:33], v[52:53], off offset:3072
	v_lshl_add_u64 v[42:43], v[38:39], 0, s[28:29]
	v_addc_co_u32_e32 v45, vcc, 0, v39, vcc
	global_load_dwordx2 v[36:37], v[38:39], off
	global_load_dwordx2 v[34:35], v[38:39], off offset:512
	global_load_dwordx2 v[40:41], v[38:39], off offset:1024
	s_nop 0
	global_load_dwordx2 v[38:39], v[38:39], off offset:1536
	s_nop 0
	global_load_dwordx2 v[60:61], v[44:45], off
	global_load_dwordx2 v[62:63], v[42:43], off offset:512
	global_load_dwordx2 v[64:65], v[42:43], off offset:1024
	global_load_dwordx2 v[66:67], v[42:43], off offset:1536
	s_mov_b32 s8, 0
	s_add_i32 s9, s0, 16
	s_mov_b32 s10, 0
	s_waitcnt vmcnt(0)
	v_mov_b64_e32 v[224:225], v[60:61]
	v_mov_b64_e32 v[226:227], v[62:63]
	v_mov_b64_e32 v[228:229], v[64:65]
	v_mov_b64_e32 v[230:231], v[66:67]
	s_branch .LBB0_1810

.LBB0_1809:
	s_add_i32 s10, s10, 1
	s_add_i32 s8, s8, 8
	s_cmpk_lg_i32 s8, 0x100
	v_mov_b64_e32 v[38:39], v[66:67]
	v_mov_b64_e32 v[40:41], v[64:65]
	v_mov_b64_e32 v[34:35], v[62:63]
	v_mov_b64_e32 v[36:37], v[60:61]
	s_waitcnt lgkmcnt(0)
	s_cbranch_scc0 .LBB0_1793
.LBB0_1810:
	s_waitcnt lgkmcnt(0)
	v_lshlrev_b32_e32 v77, 16, v37
	v_lshlrev_b32_e32 v76, 16, v36
	v_and_b32_e32 v37, 0xffff0000, v37
	v_and_b32_e32 v36, 0xffff0000, v36
	v_pk_add_f32 v[68:69], v[76:77], v[36:37]
	v_lshlrev_b32_e32 v87, 16, v35
	v_lshlrev_b32_e32 v86, 16, v34
	v_and_b32_e32 v35, 0xffff0000, v35
	v_and_b32_e32 v34, 0xffff0000, v34
	v_lshlrev_b32_e32 v46, 16, v39
	v_and_b32_e32 v48, 0xffff0000, v39
	v_add_f32_e32 v39, v68, v69
	v_pk_add_f32 v[68:69], v[86:87], v[34:35]
	v_lshlrev_b32_e32 v42, 16, v40
	v_and_b32_e32 v43, 0xffff0000, v40
	v_lshlrev_b32_e32 v40, 16, v41
	v_and_b32_e32 v41, 0xffff0000, v41
	v_pk_add_f32 v[68:69], v[68:69], v[68:69] op_sel_hi:[0,1]
	v_lshlrev_b32_e32 v44, 16, v38
	v_and_b32_e32 v38, 0xffff0000, v38
	v_add_f32_e32 v49, 0, v39
	v_add_f32_e32 v45, v42, v43
	v_add_f32_e32 v39, v40, v41
	v_mov_b32_e32 v47, v69
	v_pk_add_f32 v[70:71], v[44:45], v[38:39]
	v_pk_add_f32 v[68:69], v[46:47], v[48:49]
	s_min_u32 s0, s10, 29
	v_pk_add_f32 v[68:69], v[70:71], v[68:69]
	s_lshl_b32 s0, s0, 3
	v_add_f32_e32 v39, v68, v69
	s_add_i32 s22, s9, s0
	s_nop 0
	v_add_f32_dpp v39, v39, v39 quad_perm:[1,0,3,2] row_mask:0xf bank_mask:0xf bound_ctrl:1
	s_nop 1
	v_add_f32_dpp v39, v39, v39 quad_perm:[2,3,0,1] row_mask:0xf bank_mask:0xf bound_ctrl:1
	s_nop 1
	v_add_f32_dpp v39, v39, v39 row_half_mirror row_mask:0xf bank_mask:0xf bound_ctrl:1
	s_nop 1
	v_add_f32_dpp v39, v39, v39 row_mirror row_mask:0xf bank_mask:0xf bound_ctrl:1
	s_nop 0
	v_readlane_b32 s11, v39, 16
	v_readlane_b32 s23, v39, 48
	v_readlane_b32 s0, v39, 0
	v_readlane_b32 s1, v39, 32
	v_mov_b32_e32 v68, s11
	v_mov_b32_e32 v69, s23
	v_pk_add_f32 v[68:69], s[0:1], v[68:69]
	s_nop 0
	v_add_f32_e32 v39, v68, v69
	v_fmac_f32_e32 v36, 0xba800000, v39
	v_fmac_f32_e32 v37, 0xba800000, v39
	v_fmac_f32_e32 v77, 0xba800000, v39
	v_fmac_f32_e32 v76, 0xba800000, v39
	v_mov_b32_e32 v88, v77
	v_mov_b32_e32 v89, v37
	v_mov_b32_e32 v77, v36
	v_fmac_f32_e32 v34, 0xba800000, v39
	v_fmac_f32_e32 v35, 0xba800000, v39
	v_fmac_f32_e32 v87, 0xba800000, v39
	v_pk_mul_f32 v[68:69], v[88:89], v[88:89]
	v_pk_mul_f32 v[36:37], v[76:77], v[76:77]
	v_fmac_f32_e32 v86, 0xba800000, v39
	v_mov_b32_e32 v90, v87
	v_mov_b32_e32 v91, v35
	v_mov_b32_e32 v87, v34
	v_pk_mov_b32 v[70:71], v[36:37], v[68:69] op_sel:[1,0]
	v_mov_b32_e32 v37, v69
	v_pk_mul_f32 v[68:69], v[90:91], v[90:91]
	v_pk_mul_f32 v[34:35], v[86:87], v[86:87]
	v_pk_add_f32 v[36:37], v[70:71], v[36:37]
	v_pk_mov_b32 v[70:71], v[34:35], v[68:69] op_sel:[1,0]
	v_mov_b32_e32 v35, v69
	v_pk_add_f32 v[34:35], v[70:71], v[34:35]
	v_fmac_f32_e32 v42, 0xba800000, v39
	v_pk_add_f32 v[34:35], v[34:35], v[34:35] op_sel_hi:[0,1]
	v_fmac_f32_e32 v43, 0xba800000, v39
	v_fmac_f32_e32 v40, 0xba800000, v39
	v_mul_f32_e32 v34, v42, v42
	v_fmac_f32_e32 v41, 0xba800000, v39
	v_pk_fma_f32 v[68:69], v[42:43], v[42:43], v[34:35] op_sel_hi:[1,1,0]
	v_mul_f32_e32 v34, v40, v40
	v_pk_add_f32 v[36:37], v[36:37], v[36:37] op_sel_hi:[0,1]
	v_pk_fma_f32 v[70:71], v[40:41], v[40:41], v[34:35] op_sel_hi:[1,1,0]
	v_fmac_f32_e32 v48, 0xba800000, v39
	v_fmac_f32_e32 v46, 0xba800000, v39
	v_fmac_f32_e32 v38, 0xba800000, v39
	v_fmac_f32_e32 v44, 0xba800000, v39
	v_mul_f32_e32 v68, v44, v44
	v_mul_f32_e32 v70, v38, v38
	v_mul_f32_e32 v36, v46, v46
	v_mul_f32_e32 v34, v48, v48
	v_pk_add_f32 v[68:69], v[68:69], v[70:71]
	v_pk_add_f32 v[34:35], v[36:37], v[34:35]
	v_mov_b32_e32 v47, v48
	v_pk_add_f32 v[34:35], v[68:69], v[34:35]
	s_nop 0
	v_add_f32_e32 v34, v34, v35
	s_nop 1
	v_add_f32_dpp v34, v34, v34 quad_perm:[1,0,3,2] row_mask:0xf bank_mask:0xf bound_ctrl:1
	s_nop 1
	v_add_f32_dpp v34, v34, v34 quad_perm:[2,3,0,1] row_mask:0xf bank_mask:0xf bound_ctrl:1
	s_nop 1
	v_add_f32_dpp v34, v34, v34 row_half_mirror row_mask:0xf bank_mask:0xf bound_ctrl:1
	s_nop 1
	v_add_f32_dpp v34, v34, v34 row_mirror row_mask:0xf bank_mask:0xf bound_ctrl:1
	s_nop 0
	v_readlane_b32 s11, v34, 16
	v_readlane_b32 s23, v34, 48
	v_readlane_b32 s0, v34, 0
	v_readlane_b32 s1, v34, 32
	v_mov_b32_e32 v34, s11
	v_mov_b32_e32 v35, s23
	v_pk_add_f32 v[34:35], s[0:1], v[34:35]
	s_mov_b32 s0, 0xf800000
	v_add_f32_e32 v34, v34, v35
	v_fmamk_f32 v34, v34, 0x3a800000, v83
	s_ashr_i32 s23, s22, 31
	v_mul_f32_e32 v35, 0x4f800000, v34
	v_cmp_gt_f32_e32 vcc, s0, v34
	s_lshl_b64 s[0:1], s[22:23], 11
	s_and_b32 s11, s10, 3
	v_cndmask_b32_e32 v36, v34, v35, vcc
	v_lshl_add_u64 v[34:35], v[54:55], 0, s[0:1]
	s_waitcnt vmcnt(8)
	v_mov_b64_e32 v[66:67], v[230:231]
	v_mov_b64_e32 v[64:65], v[228:229]
	v_mov_b64_e32 v[62:63], v[226:227]
	v_mov_b64_e32 v[60:61], v[224:225]
	global_load_dwordx2 v[224:225], v[34:35], off
	global_load_dwordx2 v[226:227], v[34:35], off offset:512
	global_load_dwordx2 v[228:229], v[34:35], off offset:1024
	global_load_dwordx2 v[230:231], v[34:35], off offset:1536
	v_sqrt_f32_e32 v37, v36
	s_mul_i32 s26, s11, 0x810
	s_add_i32 s26, s87, s26
	v_add_u32_e32 v39, -1, v37
	v_fma_f32 v45, -v39, v37, v36
	v_cmp_ge_f32_e64 s[22:23], 0, v45
	v_add_u32_e32 v45, 1, v37
	s_nop 0
	v_cndmask_b32_e64 v39, v37, v39, s[22:23]
	v_fma_f32 v37, -v45, v37, v36
	v_cmp_lt_f32_e64 s[22:23], 0, v37
	s_nop 1
	v_cndmask_b32_e64 v37, v39, v45, s[22:23]
	v_mul_f32_e32 v39, 0x37800000, v37
	v_cndmask_b32_e32 v37, v37, v39, vcc
	v_cmp_class_f32_e32 vcc, v36, v84
	s_add_i32 s22, s4, s8
	s_ashr_i32 s23, s22, 31
	v_cndmask_b32_e32 v36, v37, v36, vcc
	v_div_scale_f32 v37, s[0:1], v36, v36, 1.0
	v_rcp_f32_e32 v39, v37
	s_lshl_b64 s[0:1], s[22:23], 11
	v_fma_f32 v34, -v37, v39, 1.0
	v_fmac_f32_e32 v39, v34, v39
	v_div_scale_f32 v34, vcc, 1.0, v36, 1.0
	v_mul_f32_e32 v35, v34, v39
	v_fma_f32 v45, -v37, v35, v34
	v_fmac_f32_e32 v35, v45, v39
	v_fma_f32 v34, -v37, v35, v34
	v_div_fmas_f32 v34, v34, v39, v35
	v_div_fixup_f32 v34, v34, v36, 1.0
	v_mov_b32_e32 v45, v38
	v_pk_mul_f32 v[36:37], v[76:77], v[34:35] op_sel_hi:[1,0]
	v_pk_mul_f32 v[76:77], v[88:89], v[34:35] op_sel_hi:[1,0]
	v_pk_mul_f32 v[38:39], v[44:45], v[34:35] op_sel_hi:[1,0]
	v_mov_b32_e32 v44, v78
	v_pk_fma_f32 v[76:77], v[4:5], v[76:77], v[12:13]
	v_pk_fma_f32 v[36:37], v[2:3], v[36:37], v[10:11]
	v_pk_mul_f32 v[86:87], v[86:87], v[34:35] op_sel_hi:[1,0]
	v_pk_mul_f32 v[88:89], v[90:91], v[34:35] op_sel_hi:[1,0]
	v_pk_fma_f32 v[86:87], v[6:7], v[86:87], v[14:15]
	v_pk_fma_f32 v[88:89], v[8:9], v[88:89], v[16:17]
	v_pk_mul_f32 v[42:43], v[42:43], v[34:35] op_sel_hi:[1,0]
	v_pk_mul_f32 v[40:41], v[40:41], v[34:35] op_sel_hi:[1,0]
	v_pk_mul_f32 v[34:35], v[46:47], v[34:35] op_sel_hi:[1,0]
	v_lshl_add_u32 v48, v44, 3, s26
	v_cvt_pk_bf16_f32 v44, v36, v37
	v_cvt_pk_bf16_f32 v45, v76, v77
	v_lshl_add_u64 v[46:47], v[56:57], 0, s[0:1]
	v_pk_fma_f32 v[40:41], v[20:21], v[40:41], v[28:29]
	v_pk_fma_f32 v[42:43], v[18:19], v[42:43], v[26:27]
	global_store_dwordx2 v[46:47], v[44:45], off
	ds_write_b64 v48, v[44:45] offset:33024
	v_cvt_pk_bf16_f32 v44, v86, v87
	v_cvt_pk_bf16_f32 v45, v88, v89
	v_pk_fma_f32 v[34:35], v[24:25], v[34:35], v[32:33]
	v_pk_fma_f32 v[38:39], v[22:23], v[38:39], v[30:31]
	global_store_dwordx2 v[46:47], v[44:45], off offset:512
	ds_write_b64 v48, v[44:45] offset:33536
	v_cvt_pk_bf16_f32 v44, v42, v43
	v_cvt_pk_bf16_f32 v45, v40, v41
	global_store_dwordx2 v[46:47], v[44:45], off offset:1024
	ds_write_b64 v48, v[44:45] offset:34048
	v_cvt_pk_bf16_f32 v44, v38, v39
	v_cvt_pk_bf16_f32 v45, v34, v35
	global_store_dwordx2 v[46:47], v[44:45], off offset:1536
	ds_write_b64 v48, v[44:45] offset:34560
	v_med3_f32 v36, v36, s6, v85
	v_med3_f32 v37, v37, s6, v85
	v_mov_b32_e32 v44, 0
	v_cvt_pk_fp8_f32 v44, v36, v37
	v_med3_f32 v36, v76, s6, v85
	v_med3_f32 v37, v77, s6, v85
	v_med3_f32 v45, v86, s6, v85
	v_cvt_pk_fp8_f32 v44, v36, v37 op_sel:[0,0,1]
	v_med3_f32 v46, v87, s6, v85
	v_mov_b32_e32 v47, 0
	v_cvt_pk_fp8_f32 v47, v45, v46
	s_lshl_b64 s[0:1], s[22:23], 10
	v_lshl_add_u64 v[36:37], v[58:59], 0, s[0:1]
	global_store_dword v[36:37], v44, off
	v_med3_f32 v44, v88, s6, v85
	v_med3_f32 v45, v89, s6, v85
	v_cvt_pk_fp8_f32 v47, v44, v45 op_sel:[0,0,1]
	v_med3_f32 v42, v42, s6, v85
	v_med3_f32 v43, v43, s6, v85
	v_mov_b32_e32 v44, 0
	v_cvt_pk_fp8_f32 v44, v42, v43
	v_med3_f32 v38, v38, s6, v85
	v_med3_f32 v39, v39, s6, v85
	v_mov_b32_e32 v42, 0
	v_cvt_pk_fp8_f32 v42, v38, v39
	v_med3_f32 v34, v34, s6, v85
	v_med3_f32 v35, v35, s6, v85
	v_med3_f32 v40, v40, s6, v85
	v_med3_f32 v41, v41, s6, v85
	v_cvt_pk_fp8_f32 v42, v34, v35 op_sel:[0,0,1]
	v_cvt_pk_fp8_f32 v44, v40, v41 op_sel:[0,0,1]
	s_cmp_lg_u32 s11, 3
	global_store_dword v[36:37], v47, off offset:256
	global_store_dword v[36:37], v44, off offset:512
	global_store_dword v[36:37], v42, off offset:768
	s_cbranch_scc1 .LBB0_1809
	v_mov_b32_e32 v76, v78
	s_nop 0
	v_and_b32_e32 v34, 3, v76
	v_mul_u32_u24_e32 v34, 0x810, v34
	v_and_b32_e32 v35, -16, v76
	v_add3_u32 v77, s87, v34, v35
	v_and_b32_e32 v34, 15, v76
	v_mul_u32_u24_e32 v34, 0x810, v34
	v_add3_u32 v94, 0, v34, v35
	ds_read_b128 v[34:37], v77 offset:33024
	ds_read_b128 v[38:41], v94
	s_waitcnt lgkmcnt(0)
	v_mfma_f32_16x16x32_bf16 v[34:37], v[34:37], v[38:41], 0
	ds_read_b128 v[38:41], v77 offset:33088
	ds_read_b128 v[42:45], v94 offset:64
	v_cmp_gt_i32_e32 vcc, 16, v76
	s_waitcnt lgkmcnt(0)
	v_mfma_f32_16x16x32_bf16 v[38:41], v[38:41], v[42:45], 0
	ds_read_b128 v[42:45], v77 offset:33152
	ds_read_b128 v[46:49], v94 offset:128
	s_waitcnt lgkmcnt(0)
	v_mfma_f32_16x16x32_bf16 v[42:45], v[42:45], v[46:49], 0
	ds_read_b128 v[46:49], v77 offset:33216
	ds_read_b128 v[86:89], v94 offset:192
	s_waitcnt lgkmcnt(0)
	v_mfma_f32_16x16x32_bf16 v[46:49], v[46:49], v[86:89], 0
	ds_read_b128 v[86:89], v77 offset:33280
	ds_read_b128 v[90:93], v94 offset:256
	s_waitcnt lgkmcnt(0)
	v_mfma_f32_16x16x32_bf16 v[34:37], v[86:89], v[90:93], v[34:37]
	ds_read_b128 v[86:89], v77 offset:33344
	ds_read_b128 v[90:93], v94 offset:320
	s_waitcnt lgkmcnt(0)
	v_mfma_f32_16x16x32_bf16 v[38:41], v[86:89], v[90:93], v[38:41]
	ds_read_b128 v[86:89], v77 offset:33408
	ds_read_b128 v[90:93], v94 offset:384
	s_waitcnt lgkmcnt(0)
	v_mfma_f32_16x16x32_bf16 v[42:45], v[86:89], v[90:93], v[42:45]
	ds_read_b128 v[86:89], v77 offset:33472
	ds_read_b128 v[90:93], v94 offset:448
	s_waitcnt lgkmcnt(0)
	v_mfma_f32_16x16x32_bf16 v[46:49], v[86:89], v[90:93], v[46:49]
	ds_read_b128 v[86:89], v77 offset:33536
	ds_read_b128 v[90:93], v94 offset:512
	s_waitcnt lgkmcnt(0)
	v_mfma_f32_16x16x32_bf16 v[34:37], v[86:89], v[90:93], v[34:37]
	ds_read_b128 v[86:89], v77 offset:33600
	ds_read_b128 v[90:93], v94 offset:576
	s_waitcnt lgkmcnt(0)
	v_mfma_f32_16x16x32_bf16 v[38:41], v[86:89], v[90:93], v[38:41]
	ds_read_b128 v[86:89], v77 offset:33664
	ds_read_b128 v[90:93], v94 offset:640
	s_waitcnt lgkmcnt(0)
	v_mfma_f32_16x16x32_bf16 v[42:45], v[86:89], v[90:93], v[42:45]
	ds_read_b128 v[86:89], v77 offset:33728
	ds_read_b128 v[90:93], v94 offset:704
	s_waitcnt lgkmcnt(0)
	v_mfma_f32_16x16x32_bf16 v[46:49], v[86:89], v[90:93], v[46:49]
	ds_read_b128 v[86:89], v77 offset:33792
	ds_read_b128 v[90:93], v94 offset:768
	s_waitcnt lgkmcnt(0)
	v_mfma_f32_16x16x32_bf16 v[34:37], v[86:89], v[90:93], v[34:37]
	ds_read_b128 v[86:89], v77 offset:33856
	ds_read_b128 v[90:93], v94 offset:832
	s_waitcnt lgkmcnt(0)
	v_mfma_f32_16x16x32_bf16 v[38:41], v[86:89], v[90:93], v[38:41]
	ds_read_b128 v[86:89], v77 offset:33920
	ds_read_b128 v[90:93], v94 offset:896
	s_waitcnt lgkmcnt(0)
	v_mfma_f32_16x16x32_bf16 v[42:45], v[86:89], v[90:93], v[42:45]
	ds_read_b128 v[86:89], v77 offset:33984
	ds_read_b128 v[90:93], v94 offset:960
	s_waitcnt lgkmcnt(0)
	v_mfma_f32_16x16x32_bf16 v[46:49], v[86:89], v[90:93], v[46:49]
	ds_read_b128 v[86:89], v77 offset:34048
	ds_read_b128 v[90:93], v94 offset:1024
	s_waitcnt lgkmcnt(0)
	v_mfma_f32_16x16x32_bf16 v[34:37], v[86:89], v[90:93], v[34:37]
	ds_read_b128 v[86:89], v77 offset:34112
	ds_read_b128 v[90:93], v94 offset:1088
	s_waitcnt lgkmcnt(0)
	v_mfma_f32_16x16x32_bf16 v[38:41], v[86:89], v[90:93], v[38:41]
	ds_read_b128 v[86:89], v77 offset:34176
	ds_read_b128 v[90:93], v94 offset:1152
	s_waitcnt lgkmcnt(0)
	v_mfma_f32_16x16x32_bf16 v[42:45], v[86:89], v[90:93], v[42:45]
	ds_read_b128 v[86:89], v77 offset:34240
	ds_read_b128 v[90:93], v94 offset:1216
	s_waitcnt lgkmcnt(0)
	v_mfma_f32_16x16x32_bf16 v[46:49], v[86:89], v[90:93], v[46:49]
	ds_read_b128 v[86:89], v77 offset:34304
	ds_read_b128 v[90:93], v94 offset:1280
	s_waitcnt lgkmcnt(0)
	v_mfma_f32_16x16x32_bf16 v[34:37], v[86:89], v[90:93], v[34:37]
	ds_read_b128 v[86:89], v77 offset:34368
	ds_read_b128 v[90:93], v94 offset:1344
	s_waitcnt lgkmcnt(0)
	v_mfma_f32_16x16x32_bf16 v[38:41], v[86:89], v[90:93], v[38:41]
	ds_read_b128 v[86:89], v77 offset:34432
	ds_read_b128 v[90:93], v94 offset:1408
	s_waitcnt lgkmcnt(0)
	v_mfma_f32_16x16x32_bf16 v[42:45], v[86:89], v[90:93], v[42:45]
	ds_read_b128 v[86:89], v77 offset:34496
	ds_read_b128 v[90:93], v94 offset:1472
	s_waitcnt lgkmcnt(0)
	v_mfma_f32_16x16x32_bf16 v[46:49], v[86:89], v[90:93], v[46:49]
	ds_read_b128 v[86:89], v77 offset:34560
	ds_read_b128 v[90:93], v94 offset:1536
	s_waitcnt lgkmcnt(0)
	v_mfma_f32_16x16x32_bf16 v[34:37], v[86:89], v[90:93], v[34:37]
	ds_read_b128 v[86:89], v77 offset:34624
	ds_read_b128 v[90:93], v94 offset:1600
	s_waitcnt lgkmcnt(0)
	v_mfma_f32_16x16x32_bf16 v[38:41], v[86:89], v[90:93], v[38:41]
	ds_read_b128 v[86:89], v77 offset:34688
	ds_read_b128 v[90:93], v94 offset:1664
	s_waitcnt lgkmcnt(0)
	v_mfma_f32_16x16x32_bf16 v[42:45], v[86:89], v[90:93], v[42:45]
	ds_read_b128 v[86:89], v77 offset:34752
	ds_read_b128 v[90:93], v94 offset:1728
	s_waitcnt lgkmcnt(0)
	v_mfma_f32_16x16x32_bf16 v[46:49], v[86:89], v[90:93], v[46:49]
	ds_read_b128 v[86:89], v77 offset:34816
	ds_read_b128 v[90:93], v94 offset:1792
	s_waitcnt lgkmcnt(0)
	v_mfma_f32_16x16x32_bf16 v[34:37], v[86:89], v[90:93], v[34:37]
	ds_read_b128 v[86:89], v77 offset:34880
	ds_read_b128 v[90:93], v94 offset:1856
	s_waitcnt lgkmcnt(0)
	v_mfma_f32_16x16x32_bf16 v[38:41], v[86:89], v[90:93], v[38:41]
	ds_read_b128 v[86:89], v77 offset:34944
	ds_read_b128 v[90:93], v94 offset:1920
	s_waitcnt lgkmcnt(0)
	v_mfma_f32_16x16x32_bf16 v[42:45], v[86:89], v[90:93], v[42:45]
	ds_read_b128 v[86:89], v77 offset:35008
	ds_read_b128 v[90:93], v94 offset:1984
	s_nop 1
	v_pk_add_f32 v[34:35], v[34:35], v[38:39]
	v_ashrrev_i32_e32 v77, 31, v76
	s_waitcnt lgkmcnt(0)
	v_mfma_f32_16x16x32_bf16 v[46:49], v[86:89], v[90:93], v[46:49]
	s_nop 7
	v_pk_add_f32 v[38:39], v[42:43], v[46:47]
	s_nop 0
	v_pk_add_f32 v[38:39], v[34:35], v[38:39]
	v_lshlrev_b64 v[34:35], 13, v[76:77]
	v_lshl_add_u64 v[34:35], s[30:31], 0, v[34:35]
	v_mov_b32_dpp v42, v38 quad_perm:[1,0,3,2] row_mask:0xf bank_mask:0xf bound_ctrl:1
	v_max_f32_e32 v42, v42, v42
	v_max_f32_e32 v42, v38, v42
	s_nop 1
	v_mov_b32_dpp v43, v42 quad_perm:[2,3,0,1] row_mask:0xf bank_mask:0xf bound_ctrl:1
	v_max_f32_e32 v43, v43, v43
	v_max_f32_e32 v42, v42, v43
	s_nop 1
	v_mov_b32_dpp v43, v42 row_half_mirror row_mask:0xf bank_mask:0xf bound_ctrl:1
	v_max_f32_e32 v43, v43, v43
	v_max_f32_e32 v42, v42, v43
	s_nop 1
	v_mov_b32_dpp v43, v42 row_mirror row_mask:0xf bank_mask:0xf bound_ctrl:1
	v_max_f32_e32 v43, v43, v43
	v_max_f32_e32 v42, v42, v43
	v_sub_f32_e32 v38, v38, v42
	v_mul_f32_e32 v38, 0x3fb8aa3b, v38
	v_exp_f32_e32 v38, v38
	s_nop 1
	v_add_f32_dpp v42, v38, v38 quad_perm:[1,0,3,2] row_mask:0xf bank_mask:0xf bound_ctrl:1
	s_nop 1
	v_add_f32_dpp v42, v42, v42 quad_perm:[2,3,0,1] row_mask:0xf bank_mask:0xf bound_ctrl:1
	s_nop 1
	v_add_f32_dpp v42, v42, v42 row_half_mirror row_mask:0xf bank_mask:0xf bound_ctrl:1
	s_nop 1
	v_mov_b32_dpp v43, v42 row_mirror row_mask:0xf bank_mask:0xf bound_ctrl:1
	s_and_saveexec_b64 s[34:35], vcc
	s_cbranch_execz .LBB0_1813
	v_add_f32_e32 v42, v42, v43
	v_rcp_f32_e32 v42, v42
	s_sub_i32 s11, s22, 24
	s_ashr_i32 s0, s11, 11
	s_ashr_i32 s1, s0, 31
	s_and_b32 s11, s11, 0x7ff
	s_lshl_b64 s[0:1], s[0:1], 17
	v_mul_f32_e32 v38, v38, v42
	v_lshl_add_u64 v[42:43], v[34:35], 0, s[0:1]
	s_lshl_b32 s26, s11, 2
	v_lshl_add_u64 v[42:43], v[42:43], 0, s[26:27]
	global_store_dword v[42:43], v38, off
.LBB0_1813:
	s_or_b64 exec, exec, s[34:35]
	v_mov_b32_dpp v38, v39 quad_perm:[1,0,3,2] row_mask:0xf bank_mask:0xf bound_ctrl:1
	v_max_f32_e32 v38, v38, v38
	v_max_f32_e32 v42, v39, v39
	v_max_f32_e32 v38, v42, v38
	v_pk_add_f32 v[36:37], v[36:37], v[40:41]
	v_pk_add_f32 v[40:41], v[44:45], v[48:49]
	v_mov_b32_dpp v42, v38 quad_perm:[2,3,0,1] row_mask:0xf bank_mask:0xf bound_ctrl:1
	v_max_f32_e32 v42, v42, v42
	v_max_f32_e32 v38, v38, v42
	v_pk_add_f32 v[36:37], v[36:37], v[40:41]
	s_nop 0
	v_mov_b32_dpp v42, v38 row_half_mirror row_mask:0xf bank_mask:0xf bound_ctrl:1
	v_max_f32_e32 v42, v42, v42
	v_max_f32_e32 v38, v38, v42
	s_nop 1
	v_mov_b32_dpp v42, v38 row_mirror row_mask:0xf bank_mask:0xf bound_ctrl:1
	v_max_f32_e32 v42, v42, v42
	v_max_f32_e32 v38, v38, v42
	v_sub_f32_e32 v38, v39, v38
	v_mul_f32_e32 v38, 0x3fb8aa3b, v38
	v_exp_f32_e32 v38, v38
	s_nop 1
	v_add_f32_dpp v39, v38, v38 quad_perm:[1,0,3,2] row_mask:0xf bank_mask:0xf bound_ctrl:1
	s_nop 1
	v_add_f32_dpp v39, v39, v39 quad_perm:[2,3,0,1] row_mask:0xf bank_mask:0xf bound_ctrl:1
	s_nop 1
	v_add_f32_dpp v39, v39, v39 row_half_mirror row_mask:0xf bank_mask:0xf bound_ctrl:1
	s_nop 1
	v_mov_b32_dpp v40, v39 row_mirror row_mask:0xf bank_mask:0xf bound_ctrl:1
	s_and_saveexec_b64 s[34:35], vcc
	s_cbranch_execz .LBB0_1815
	v_add_f32_e32 v39, v39, v40
	v_rcp_f32_e32 v39, v39
	s_add_i32 s11, s22, -16
	s_ashr_i32 s0, s11, 11
	s_ashr_i32 s1, s0, 31
	s_and_b32 s11, s11, 0x7ff
	s_lshl_b64 s[0:1], s[0:1], 17
	v_mul_f32_e32 v40, v38, v39
	v_lshl_add_u64 v[38:39], v[34:35], 0, s[0:1]
	s_lshl_b32 s26, s11, 2
	v_lshl_add_u64 v[38:39], v[38:39], 0, s[26:27]
	global_store_dword v[38:39], v40, off
.LBB0_1815:
	s_or_b64 exec, exec, s[34:35]
	v_mov_b32_dpp v38, v36 quad_perm:[1,0,3,2] row_mask:0xf bank_mask:0xf bound_ctrl:1
	v_max_f32_e32 v38, v38, v38
	v_max_f32_e32 v39, v36, v36
	v_max_f32_e32 v38, v39, v38
	s_nop 1
	v_mov_b32_dpp v39, v38 quad_perm:[2,3,0,1] row_mask:0xf bank_mask:0xf bound_ctrl:1
	v_max_f32_e32 v39, v39, v39
	v_max_f32_e32 v38, v38, v39
	s_nop 1
	v_mov_b32_dpp v39, v38 row_half_mirror row_mask:0xf bank_mask:0xf bound_ctrl:1
	v_max_f32_e32 v39, v39, v39
	v_max_f32_e32 v38, v38, v39
	s_nop 1
	v_mov_b32_dpp v39, v38 row_mirror row_mask:0xf bank_mask:0xf bound_ctrl:1
	v_max_f32_e32 v39, v39, v39
	v_max_f32_e32 v38, v38, v39
	v_sub_f32_e32 v36, v36, v38
	v_mul_f32_e32 v36, 0x3fb8aa3b, v36
	v_exp_f32_e32 v36, v36
	s_nop 1
	v_add_f32_dpp v38, v36, v36 quad_perm:[1,0,3,2] row_mask:0xf bank_mask:0xf bound_ctrl:1
	s_nop 1
	v_add_f32_dpp v38, v38, v38 quad_perm:[2,3,0,1] row_mask:0xf bank_mask:0xf bound_ctrl:1
	s_nop 1
	v_add_f32_dpp v38, v38, v38 row_half_mirror row_mask:0xf bank_mask:0xf bound_ctrl:1
	s_nop 1
	v_mov_b32_dpp v39, v38 row_mirror row_mask:0xf bank_mask:0xf bound_ctrl:1
	s_and_saveexec_b64 s[34:35], vcc
	s_cbranch_execz .LBB0_1817
	v_add_f32_e32 v38, v38, v39
	v_rcp_f32_e32 v38, v38
	s_add_i32 s11, s22, -8
	s_ashr_i32 s0, s11, 11
	s_ashr_i32 s1, s0, 31
	s_and_b32 s11, s11, 0x7ff
	s_lshl_b64 s[0:1], s[0:1], 17
	v_mul_f32_e32 v36, v36, v38
	v_lshl_add_u64 v[38:39], v[34:35], 0, s[0:1]
	s_lshl_b32 s26, s11, 2
	v_lshl_add_u64 v[38:39], v[38:39], 0, s[26:27]
	global_store_dword v[38:39], v36, off
.LBB0_1817:
	s_or_b64 exec, exec, s[34:35]
	v_mov_b32_dpp v36, v37 quad_perm:[1,0,3,2] row_mask:0xf bank_mask:0xf bound_ctrl:1
	v_max_f32_e32 v36, v36, v36
	v_max_f32_e32 v38, v37, v37
	v_max_f32_e32 v36, v38, v36
	s_nop 1
	v_mov_b32_dpp v38, v36 quad_perm:[2,3,0,1] row_mask:0xf bank_mask:0xf bound_ctrl:1
	v_max_f32_e32 v38, v38, v38
	v_max_f32_e32 v36, v36, v38
	s_nop 1
	v_mov_b32_dpp v38, v36 row_half_mirror row_mask:0xf bank_mask:0xf bound_ctrl:1
	v_max_f32_e32 v38, v38, v38
	v_max_f32_e32 v36, v36, v38
	s_nop 1
	v_mov_b32_dpp v38, v36 row_mirror row_mask:0xf bank_mask:0xf bound_ctrl:1
	v_max_f32_e32 v38, v38, v38
	v_max_f32_e32 v36, v36, v38
	v_sub_f32_e32 v36, v37, v36
	v_mul_f32_e32 v36, 0x3fb8aa3b, v36
	v_exp_f32_e32 v36, v36
	s_nop 1
	v_add_f32_dpp v37, v36, v36 quad_perm:[1,0,3,2] row_mask:0xf bank_mask:0xf bound_ctrl:1
	s_nop 1
	v_add_f32_dpp v37, v37, v37 quad_perm:[2,3,0,1] row_mask:0xf bank_mask:0xf bound_ctrl:1
	s_nop 1
	v_add_f32_dpp v37, v37, v37 row_half_mirror row_mask:0xf bank_mask:0xf bound_ctrl:1
	s_nop 1
	v_mov_b32_dpp v38, v37 row_mirror row_mask:0xf bank_mask:0xf bound_ctrl:1
	s_and_saveexec_b64 s[34:35], vcc
	s_cbranch_execz .LBB0_1808
	v_add_f32_e32 v37, v37, v38
	v_rcp_f32_e32 v37, v37
	s_ashr_i32 s0, s22, 11
	s_ashr_i32 s1, s0, 31
	s_and_b32 s11, s22, 0x7ff
	s_lshl_b64 s[0:1], s[0:1], 17
	v_lshl_add_u64 v[34:35], v[34:35], 0, s[0:1]
	s_lshl_b32 s26, s11, 2
	v_mul_f32_e32 v36, v36, v37
	v_lshl_add_u64 v[34:35], v[34:35], 0, s[26:27]
	global_store_dword v[34:35], v36, off
	s_branch .LBB0_1808

.LBB0_2516:
	s_or_b64 exec, exec, s[18:19]
	s_lshl_b32 s0, s9, 8
	s_add_i32 s0, s0, s97
	s_ashr_i32 s1, s0, 31
	s_lshl_b64 s[18:19], s[0:1], 11
	v_lshl_add_u64 v[38:39], v[54:55], 0, s[18:19]
	s_mov_b64 s[18:19], 0x4000
	v_add_co_u32_e32 v44, vcc, 0x4000, v38
	s_waitcnt lgkmcnt(0)
	s_barrier
	global_load_dwordx4 v[2:5], v[50:51], off
	global_load_dwordx4 v[6:9], v[50:51], off offset:1024
	global_load_dwordx4 v[10:13], v[52:53], off
	global_load_dwordx4 v[14:17], v[52:53], off offset:1024
	global_load_dwordx4 v[18:21], v[50:51], off offset:2048
	global_load_dwordx4 v[22:25], v[50:51], off offset:3072
	global_load_dwordx4 v[26:29], v[52:53], off offset:2048
	global_load_dwordx4 v[30:33], v[52:53], off offset:3072
	v_lshl_add_u64 v[42:43], v[38:39], 0, s[18:19]
	v_addc_co_u32_e32 v45, vcc, 0, v39, vcc
	global_load_dwordx2 v[36:37], v[38:39], off
	global_load_dwordx2 v[34:35], v[38:39], off offset:512
	global_load_dwordx2 v[40:41], v[38:39], off offset:1024
	s_nop 0
	global_load_dwordx2 v[38:39], v[38:39], off offset:1536
	s_nop 0
	global_load_dwordx2 v[60:61], v[44:45], off
	global_load_dwordx2 v[62:63], v[42:43], off offset:512
	global_load_dwordx2 v[64:65], v[42:43], off offset:1024
	global_load_dwordx2 v[66:67], v[42:43], off offset:1536
	s_mov_b32 s28, 0
	s_add_i32 s29, s0, 16
	s_mov_b32 s30, 0
	s_waitcnt vmcnt(0)
	v_mov_b64_e32 v[224:225], v[60:61]
	v_mov_b64_e32 v[226:227], v[62:63]
	v_mov_b64_e32 v[228:229], v[64:65]
	v_mov_b64_e32 v[230:231], v[66:67]
	s_branch .LBB0_2519

.LBB0_2518:
	s_add_i32 s30, s30, 1
	s_add_i32 s28, s28, 8
	s_cmpk_lg_i32 s28, 0x100
	v_mov_b64_e32 v[38:39], v[66:67]
	v_mov_b64_e32 v[40:41], v[64:65]
	v_mov_b64_e32 v[34:35], v[62:63]
	v_mov_b64_e32 v[36:37], v[60:61]
	s_waitcnt lgkmcnt(0)
	s_cbranch_scc0 .LBB0_2502
.LBB0_2519:
	s_waitcnt lgkmcnt(0)
	v_lshlrev_b32_e32 v77, 16, v37
	v_lshlrev_b32_e32 v76, 16, v36
	v_and_b32_e32 v37, 0xffff0000, v37
	v_and_b32_e32 v36, 0xffff0000, v36
	v_pk_add_f32 v[68:69], v[76:77], v[36:37]
	v_lshlrev_b32_e32 v87, 16, v35
	v_lshlrev_b32_e32 v86, 16, v34
	v_and_b32_e32 v35, 0xffff0000, v35
	v_and_b32_e32 v34, 0xffff0000, v34
	v_lshlrev_b32_e32 v46, 16, v39
	v_and_b32_e32 v48, 0xffff0000, v39
	v_add_f32_e32 v39, v68, v69
	v_pk_add_f32 v[68:69], v[86:87], v[34:35]
	v_lshlrev_b32_e32 v42, 16, v40
	v_and_b32_e32 v43, 0xffff0000, v40
	v_lshlrev_b32_e32 v40, 16, v41
	v_and_b32_e32 v41, 0xffff0000, v41
	v_pk_add_f32 v[68:69], v[68:69], v[68:69] op_sel_hi:[0,1]
	v_lshlrev_b32_e32 v44, 16, v38
	v_and_b32_e32 v38, 0xffff0000, v38
	v_add_f32_e32 v49, 0, v39
	v_add_f32_e32 v45, v42, v43
	v_add_f32_e32 v39, v40, v41
	v_mov_b32_e32 v47, v69
	v_pk_add_f32 v[70:71], v[44:45], v[38:39]
	v_pk_add_f32 v[68:69], v[46:47], v[48:49]
	s_min_u32 s0, s30, 29
	v_pk_add_f32 v[68:69], v[70:71], v[68:69]
	s_lshl_b32 s0, s0, 3
	v_add_f32_e32 v39, v68, v69
	s_add_i32 s18, s29, s0
	s_nop 0
	v_add_f32_dpp v39, v39, v39 quad_perm:[1,0,3,2] row_mask:0xf bank_mask:0xf bound_ctrl:1
	s_nop 1
	v_add_f32_dpp v39, v39, v39 quad_perm:[2,3,0,1] row_mask:0xf bank_mask:0xf bound_ctrl:1
	s_nop 1
	v_add_f32_dpp v39, v39, v39 row_half_mirror row_mask:0xf bank_mask:0xf bound_ctrl:1
	s_nop 1
	v_add_f32_dpp v39, v39, v39 row_mirror row_mask:0xf bank_mask:0xf bound_ctrl:1
	s_nop 0
	v_readlane_b32 s19, v39, 16
	v_readlane_b32 s22, v39, 48
	v_readlane_b32 s0, v39, 0
	v_readlane_b32 s1, v39, 32
	v_mov_b32_e32 v68, s19
	v_mov_b32_e32 v69, s22
	v_pk_add_f32 v[68:69], s[0:1], v[68:69]
	s_nop 0
	v_add_f32_e32 v39, v68, v69
	v_fmac_f32_e32 v36, 0xba800000, v39
	v_fmac_f32_e32 v37, 0xba800000, v39
	v_fmac_f32_e32 v77, 0xba800000, v39
	v_fmac_f32_e32 v76, 0xba800000, v39
	v_mov_b32_e32 v88, v77
	v_mov_b32_e32 v89, v37
	v_mov_b32_e32 v77, v36
	v_fmac_f32_e32 v34, 0xba800000, v39
	v_fmac_f32_e32 v35, 0xba800000, v39
	v_fmac_f32_e32 v87, 0xba800000, v39
	v_pk_mul_f32 v[68:69], v[88:89], v[88:89]
	v_pk_mul_f32 v[36:37], v[76:77], v[76:77]
	v_fmac_f32_e32 v86, 0xba800000, v39
	v_mov_b32_e32 v90, v87
	v_mov_b32_e32 v91, v35
	v_mov_b32_e32 v87, v34
	v_pk_mov_b32 v[70:71], v[36:37], v[68:69] op_sel:[1,0]
	v_mov_b32_e32 v37, v69
	v_pk_mul_f32 v[68:69], v[90:91], v[90:91]
	v_pk_mul_f32 v[34:35], v[86:87], v[86:87]
	v_pk_add_f32 v[36:37], v[70:71], v[36:37]
	v_pk_mov_b32 v[70:71], v[34:35], v[68:69] op_sel:[1,0]
	v_mov_b32_e32 v35, v69
	v_pk_add_f32 v[34:35], v[70:71], v[34:35]
	v_fmac_f32_e32 v42, 0xba800000, v39
	v_pk_add_f32 v[34:35], v[34:35], v[34:35] op_sel_hi:[0,1]
	v_fmac_f32_e32 v43, 0xba800000, v39
	v_fmac_f32_e32 v40, 0xba800000, v39
	v_mul_f32_e32 v34, v42, v42
	v_fmac_f32_e32 v41, 0xba800000, v39
	v_pk_fma_f32 v[68:69], v[42:43], v[42:43], v[34:35] op_sel_hi:[1,1,0]
	v_mul_f32_e32 v34, v40, v40
	v_pk_add_f32 v[36:37], v[36:37], v[36:37] op_sel_hi:[0,1]
	v_pk_fma_f32 v[70:71], v[40:41], v[40:41], v[34:35] op_sel_hi:[1,1,0]
	v_fmac_f32_e32 v48, 0xba800000, v39
	v_fmac_f32_e32 v46, 0xba800000, v39
	v_fmac_f32_e32 v38, 0xba800000, v39
	v_fmac_f32_e32 v44, 0xba800000, v39
	v_mul_f32_e32 v68, v44, v44
	v_mul_f32_e32 v70, v38, v38
	v_mul_f32_e32 v36, v46, v46
	v_mul_f32_e32 v34, v48, v48
	v_pk_add_f32 v[68:69], v[68:69], v[70:71]
	v_pk_add_f32 v[34:35], v[36:37], v[34:35]
	v_mov_b32_e32 v47, v48
	v_pk_add_f32 v[34:35], v[68:69], v[34:35]
	s_nop 0
	v_add_f32_e32 v34, v34, v35
	s_nop 1
	v_add_f32_dpp v34, v34, v34 quad_perm:[1,0,3,2] row_mask:0xf bank_mask:0xf bound_ctrl:1
	s_nop 1
	v_add_f32_dpp v34, v34, v34 quad_perm:[2,3,0,1] row_mask:0xf bank_mask:0xf bound_ctrl:1
	s_nop 1
	v_add_f32_dpp v34, v34, v34 row_half_mirror row_mask:0xf bank_mask:0xf bound_ctrl:1
	s_nop 1
	v_add_f32_dpp v34, v34, v34 row_mirror row_mask:0xf bank_mask:0xf bound_ctrl:1
	s_nop 0
	v_readlane_b32 s19, v34, 16
	v_readlane_b32 s22, v34, 48
	v_readlane_b32 s0, v34, 0
	v_readlane_b32 s1, v34, 32
	v_mov_b32_e32 v34, s19
	v_mov_b32_e32 v35, s22
	v_pk_add_f32 v[34:35], s[0:1], v[34:35]
	s_mov_b32 s0, 0xf800000
	v_add_f32_e32 v34, v34, v35
	v_fmamk_f32 v34, v34, 0x3a800000, v83
	s_ashr_i32 s19, s18, 31
	v_mul_f32_e32 v35, 0x4f800000, v34
	v_cmp_gt_f32_e32 vcc, s0, v34
	s_lshl_b64 s[0:1], s[18:19], 11
	s_and_b32 s22, s30, 3
	v_cndmask_b32_e32 v36, v34, v35, vcc
	v_lshl_add_u64 v[34:35], v[54:55], 0, s[0:1]
	s_waitcnt vmcnt(8)
	v_mov_b64_e32 v[66:67], v[230:231]
	v_mov_b64_e32 v[64:65], v[228:229]
	v_mov_b64_e32 v[62:63], v[226:227]
	v_mov_b64_e32 v[60:61], v[224:225]
	global_load_dwordx2 v[224:225], v[34:35], off
	global_load_dwordx2 v[226:227], v[34:35], off offset:512
	global_load_dwordx2 v[228:229], v[34:35], off offset:1024
	global_load_dwordx2 v[230:231], v[34:35], off offset:1536
	v_sqrt_f32_e32 v37, v36
	s_mul_i32 s26, s22, 0x810
	s_add_i32 s26, s87, s26
	v_add_u32_e32 v39, -1, v37
	v_fma_f32 v45, -v39, v37, v36
	v_cmp_ge_f32_e64 s[18:19], 0, v45
	v_add_u32_e32 v45, 1, v37
	s_nop 0
	v_cndmask_b32_e64 v39, v37, v39, s[18:19]
	v_fma_f32 v37, -v45, v37, v36
	v_cmp_lt_f32_e64 s[18:19], 0, v37
	s_nop 1
	v_cndmask_b32_e64 v37, v39, v45, s[18:19]
	v_mul_f32_e32 v39, 0x37800000, v37
	v_cndmask_b32_e32 v37, v37, v39, vcc
	v_cmp_class_f32_e32 vcc, v36, v84
	s_add_i32 s18, s4, s28
	s_ashr_i32 s19, s18, 31
	v_cndmask_b32_e32 v36, v37, v36, vcc
	v_div_scale_f32 v37, s[0:1], v36, v36, 1.0
	v_rcp_f32_e32 v39, v37
	s_lshl_b64 s[0:1], s[18:19], 11
	v_fma_f32 v34, -v37, v39, 1.0
	v_fmac_f32_e32 v39, v34, v39
	v_div_scale_f32 v34, vcc, 1.0, v36, 1.0
	v_mul_f32_e32 v35, v34, v39
	v_fma_f32 v45, -v37, v35, v34
	v_fmac_f32_e32 v35, v45, v39
	v_fma_f32 v34, -v37, v35, v34
	v_div_fmas_f32 v34, v34, v39, v35
	v_div_fixup_f32 v34, v34, v36, 1.0
	v_mov_b32_e32 v45, v38
	v_pk_mul_f32 v[36:37], v[76:77], v[34:35] op_sel_hi:[1,0]
	v_pk_mul_f32 v[76:77], v[88:89], v[34:35] op_sel_hi:[1,0]
	v_pk_mul_f32 v[38:39], v[44:45], v[34:35] op_sel_hi:[1,0]
	v_mov_b32_e32 v44, v78
	v_pk_fma_f32 v[76:77], v[4:5], v[76:77], v[12:13]
	v_pk_fma_f32 v[36:37], v[2:3], v[36:37], v[10:11]
	v_pk_mul_f32 v[86:87], v[86:87], v[34:35] op_sel_hi:[1,0]
	v_pk_mul_f32 v[88:89], v[90:91], v[34:35] op_sel_hi:[1,0]
	v_pk_fma_f32 v[86:87], v[6:7], v[86:87], v[14:15]
	v_pk_fma_f32 v[88:89], v[8:9], v[88:89], v[16:17]
	v_pk_mul_f32 v[42:43], v[42:43], v[34:35] op_sel_hi:[1,0]
	v_pk_mul_f32 v[40:41], v[40:41], v[34:35] op_sel_hi:[1,0]
	v_pk_mul_f32 v[34:35], v[46:47], v[34:35] op_sel_hi:[1,0]
	v_lshl_add_u32 v48, v44, 3, s26
	v_cvt_pk_bf16_f32 v44, v36, v37
	v_cvt_pk_bf16_f32 v45, v76, v77
	v_lshl_add_u64 v[46:47], v[56:57], 0, s[0:1]
	v_pk_fma_f32 v[40:41], v[20:21], v[40:41], v[28:29]
	v_pk_fma_f32 v[42:43], v[18:19], v[42:43], v[26:27]
	global_store_dwordx2 v[46:47], v[44:45], off
	ds_write_b64 v48, v[44:45] offset:33024
	v_cvt_pk_bf16_f32 v44, v86, v87
	v_cvt_pk_bf16_f32 v45, v88, v89
	v_pk_fma_f32 v[34:35], v[24:25], v[34:35], v[32:33]
	v_pk_fma_f32 v[38:39], v[22:23], v[38:39], v[30:31]
	global_store_dwordx2 v[46:47], v[44:45], off offset:512
	ds_write_b64 v48, v[44:45] offset:33536
	v_cvt_pk_bf16_f32 v44, v42, v43
	v_cvt_pk_bf16_f32 v45, v40, v41
	global_store_dwordx2 v[46:47], v[44:45], off offset:1024
	ds_write_b64 v48, v[44:45] offset:34048
	v_cvt_pk_bf16_f32 v44, v38, v39
	v_cvt_pk_bf16_f32 v45, v34, v35
	global_store_dwordx2 v[46:47], v[44:45], off offset:1536
	ds_write_b64 v48, v[44:45] offset:34560
	v_med3_f32 v36, v36, s8, v85
	v_med3_f32 v37, v37, s8, v85
	v_mov_b32_e32 v44, 0
	v_cvt_pk_fp8_f32 v44, v36, v37
	v_med3_f32 v36, v76, s8, v85
	v_med3_f32 v37, v77, s8, v85
	v_med3_f32 v45, v86, s8, v85
	v_cvt_pk_fp8_f32 v44, v36, v37 op_sel:[0,0,1]
	v_med3_f32 v46, v87, s8, v85
	v_mov_b32_e32 v47, 0
	v_cvt_pk_fp8_f32 v47, v45, v46
	s_lshl_b64 s[0:1], s[18:19], 10
	v_lshl_add_u64 v[36:37], v[58:59], 0, s[0:1]
	global_store_dword v[36:37], v44, off
	v_med3_f32 v44, v88, s8, v85
	v_med3_f32 v45, v89, s8, v85
	v_cvt_pk_fp8_f32 v47, v44, v45 op_sel:[0,0,1]
	v_med3_f32 v42, v42, s8, v85
	v_med3_f32 v43, v43, s8, v85
	v_mov_b32_e32 v44, 0
	v_cvt_pk_fp8_f32 v44, v42, v43
	v_med3_f32 v38, v38, s8, v85
	v_med3_f32 v39, v39, s8, v85
	v_mov_b32_e32 v42, 0
	v_cvt_pk_fp8_f32 v42, v38, v39
	v_med3_f32 v34, v34, s8, v85
	v_med3_f32 v35, v35, s8, v85
	v_med3_f32 v40, v40, s8, v85
	v_med3_f32 v41, v41, s8, v85
	v_cvt_pk_fp8_f32 v42, v34, v35 op_sel:[0,0,1]
	v_cvt_pk_fp8_f32 v44, v40, v41 op_sel:[0,0,1]
	s_cmp_lg_u32 s22, 3
	global_store_dword v[36:37], v47, off offset:256
	global_store_dword v[36:37], v44, off offset:512
	global_store_dword v[36:37], v42, off offset:768
	s_cbranch_scc1 .LBB0_2518
	v_mov_b32_e32 v76, v78
	s_nop 0
	v_and_b32_e32 v34, 3, v76
	v_mul_u32_u24_e32 v34, 0x810, v34
	v_and_b32_e32 v35, -16, v76
	v_add3_u32 v77, s87, v34, v35
	v_and_b32_e32 v34, 15, v76
	v_mul_u32_u24_e32 v34, 0x810, v34
	v_add3_u32 v94, 0, v34, v35
	ds_read_b128 v[34:37], v77 offset:33024
	ds_read_b128 v[38:41], v94
	s_waitcnt lgkmcnt(0)
	v_mfma_f32_16x16x32_bf16 v[34:37], v[34:37], v[38:41], 0
	ds_read_b128 v[38:41], v77 offset:33088
	ds_read_b128 v[42:45], v94 offset:64
	v_cmp_gt_i32_e32 vcc, 16, v76
	s_waitcnt lgkmcnt(0)
	v_mfma_f32_16x16x32_bf16 v[38:41], v[38:41], v[42:45], 0
	ds_read_b128 v[42:45], v77 offset:33152
	ds_read_b128 v[46:49], v94 offset:128
	s_waitcnt lgkmcnt(0)
	v_mfma_f32_16x16x32_bf16 v[42:45], v[42:45], v[46:49], 0
	ds_read_b128 v[46:49], v77 offset:33216
	ds_read_b128 v[86:89], v94 offset:192
	s_waitcnt lgkmcnt(0)
	v_mfma_f32_16x16x32_bf16 v[46:49], v[46:49], v[86:89], 0
	ds_read_b128 v[86:89], v77 offset:33280
	ds_read_b128 v[90:93], v94 offset:256
	s_waitcnt lgkmcnt(0)
	v_mfma_f32_16x16x32_bf16 v[34:37], v[86:89], v[90:93], v[34:37]
	ds_read_b128 v[86:89], v77 offset:33344
	ds_read_b128 v[90:93], v94 offset:320
	s_waitcnt lgkmcnt(0)
	v_mfma_f32_16x16x32_bf16 v[38:41], v[86:89], v[90:93], v[38:41]
	ds_read_b128 v[86:89], v77 offset:33408
	ds_read_b128 v[90:93], v94 offset:384
	s_waitcnt lgkmcnt(0)
	v_mfma_f32_16x16x32_bf16 v[42:45], v[86:89], v[90:93], v[42:45]
	ds_read_b128 v[86:89], v77 offset:33472
	ds_read_b128 v[90:93], v94 offset:448
	s_waitcnt lgkmcnt(0)
	v_mfma_f32_16x16x32_bf16 v[46:49], v[86:89], v[90:93], v[46:49]
	ds_read_b128 v[86:89], v77 offset:33536
	ds_read_b128 v[90:93], v94 offset:512
	s_waitcnt lgkmcnt(0)
	v_mfma_f32_16x16x32_bf16 v[34:37], v[86:89], v[90:93], v[34:37]
	ds_read_b128 v[86:89], v77 offset:33600
	ds_read_b128 v[90:93], v94 offset:576
	s_waitcnt lgkmcnt(0)
	v_mfma_f32_16x16x32_bf16 v[38:41], v[86:89], v[90:93], v[38:41]
	ds_read_b128 v[86:89], v77 offset:33664
	ds_read_b128 v[90:93], v94 offset:640
	s_waitcnt lgkmcnt(0)
	v_mfma_f32_16x16x32_bf16 v[42:45], v[86:89], v[90:93], v[42:45]
	ds_read_b128 v[86:89], v77 offset:33728
	ds_read_b128 v[90:93], v94 offset:704
	s_waitcnt lgkmcnt(0)
	v_mfma_f32_16x16x32_bf16 v[46:49], v[86:89], v[90:93], v[46:49]
	ds_read_b128 v[86:89], v77 offset:33792
	ds_read_b128 v[90:93], v94 offset:768
	s_waitcnt lgkmcnt(0)
	v_mfma_f32_16x16x32_bf16 v[34:37], v[86:89], v[90:93], v[34:37]
	ds_read_b128 v[86:89], v77 offset:33856
	ds_read_b128 v[90:93], v94 offset:832
	s_waitcnt lgkmcnt(0)
	v_mfma_f32_16x16x32_bf16 v[38:41], v[86:89], v[90:93], v[38:41]
	ds_read_b128 v[86:89], v77 offset:33920
	ds_read_b128 v[90:93], v94 offset:896
	s_waitcnt lgkmcnt(0)
	v_mfma_f32_16x16x32_bf16 v[42:45], v[86:89], v[90:93], v[42:45]
	ds_read_b128 v[86:89], v77 offset:33984
	ds_read_b128 v[90:93], v94 offset:960
	s_waitcnt lgkmcnt(0)
	v_mfma_f32_16x16x32_bf16 v[46:49], v[86:89], v[90:93], v[46:49]
	ds_read_b128 v[86:89], v77 offset:34048
	ds_read_b128 v[90:93], v94 offset:1024
	s_waitcnt lgkmcnt(0)
	v_mfma_f32_16x16x32_bf16 v[34:37], v[86:89], v[90:93], v[34:37]
	ds_read_b128 v[86:89], v77 offset:34112
	ds_read_b128 v[90:93], v94 offset:1088
	s_waitcnt lgkmcnt(0)
	v_mfma_f32_16x16x32_bf16 v[38:41], v[86:89], v[90:93], v[38:41]
	ds_read_b128 v[86:89], v77 offset:34176
	ds_read_b128 v[90:93], v94 offset:1152
	s_waitcnt lgkmcnt(0)
	v_mfma_f32_16x16x32_bf16 v[42:45], v[86:89], v[90:93], v[42:45]
	ds_read_b128 v[86:89], v77 offset:34240
	ds_read_b128 v[90:93], v94 offset:1216
	s_waitcnt lgkmcnt(0)
	v_mfma_f32_16x16x32_bf16 v[46:49], v[86:89], v[90:93], v[46:49]
	ds_read_b128 v[86:89], v77 offset:34304
	ds_read_b128 v[90:93], v94 offset:1280
	s_waitcnt lgkmcnt(0)
	v_mfma_f32_16x16x32_bf16 v[34:37], v[86:89], v[90:93], v[34:37]
	ds_read_b128 v[86:89], v77 offset:34368
	ds_read_b128 v[90:93], v94 offset:1344
	s_waitcnt lgkmcnt(0)
	v_mfma_f32_16x16x32_bf16 v[38:41], v[86:89], v[90:93], v[38:41]
	ds_read_b128 v[86:89], v77 offset:34432
	ds_read_b128 v[90:93], v94 offset:1408
	s_waitcnt lgkmcnt(0)
	v_mfma_f32_16x16x32_bf16 v[42:45], v[86:89], v[90:93], v[42:45]
	ds_read_b128 v[86:89], v77 offset:34496
	ds_read_b128 v[90:93], v94 offset:1472
	s_waitcnt lgkmcnt(0)
	v_mfma_f32_16x16x32_bf16 v[46:49], v[86:89], v[90:93], v[46:49]
	ds_read_b128 v[86:89], v77 offset:34560
	ds_read_b128 v[90:93], v94 offset:1536
	s_waitcnt lgkmcnt(0)
	v_mfma_f32_16x16x32_bf16 v[34:37], v[86:89], v[90:93], v[34:37]
	ds_read_b128 v[86:89], v77 offset:34624
	ds_read_b128 v[90:93], v94 offset:1600
	s_waitcnt lgkmcnt(0)
	v_mfma_f32_16x16x32_bf16 v[38:41], v[86:89], v[90:93], v[38:41]
	ds_read_b128 v[86:89], v77 offset:34688
	ds_read_b128 v[90:93], v94 offset:1664
	s_waitcnt lgkmcnt(0)
	v_mfma_f32_16x16x32_bf16 v[42:45], v[86:89], v[90:93], v[42:45]
	ds_read_b128 v[86:89], v77 offset:34752
	ds_read_b128 v[90:93], v94 offset:1728
	s_waitcnt lgkmcnt(0)
	v_mfma_f32_16x16x32_bf16 v[46:49], v[86:89], v[90:93], v[46:49]
	ds_read_b128 v[86:89], v77 offset:34816
	ds_read_b128 v[90:93], v94 offset:1792
	s_waitcnt lgkmcnt(0)
	v_mfma_f32_16x16x32_bf16 v[34:37], v[86:89], v[90:93], v[34:37]
	ds_read_b128 v[86:89], v77 offset:34880
	ds_read_b128 v[90:93], v94 offset:1856
	s_waitcnt lgkmcnt(0)
	v_mfma_f32_16x16x32_bf16 v[38:41], v[86:89], v[90:93], v[38:41]
	ds_read_b128 v[86:89], v77 offset:34944
	ds_read_b128 v[90:93], v94 offset:1920
	s_waitcnt lgkmcnt(0)
	v_mfma_f32_16x16x32_bf16 v[42:45], v[86:89], v[90:93], v[42:45]
	ds_read_b128 v[86:89], v77 offset:35008
	ds_read_b128 v[90:93], v94 offset:1984
	s_nop 1
	v_pk_add_f32 v[34:35], v[34:35], v[38:39]
	v_ashrrev_i32_e32 v77, 31, v76
	s_waitcnt lgkmcnt(0)
	v_mfma_f32_16x16x32_bf16 v[46:49], v[86:89], v[90:93], v[46:49]
	s_nop 7
	v_pk_add_f32 v[38:39], v[42:43], v[46:47]
	s_nop 0
	v_pk_add_f32 v[38:39], v[34:35], v[38:39]
	v_lshlrev_b64 v[34:35], 13, v[76:77]
	v_lshl_add_u64 v[34:35], s[24:25], 0, v[34:35]
	v_mov_b32_dpp v42, v38 quad_perm:[1,0,3,2] row_mask:0xf bank_mask:0xf bound_ctrl:1
	v_max_f32_e32 v42, v42, v42
	v_max_f32_e32 v42, v38, v42
	s_nop 1
	v_mov_b32_dpp v43, v42 quad_perm:[2,3,0,1] row_mask:0xf bank_mask:0xf bound_ctrl:1
	v_max_f32_e32 v43, v43, v43
	v_max_f32_e32 v42, v42, v43
	s_nop 1
	v_mov_b32_dpp v43, v42 row_half_mirror row_mask:0xf bank_mask:0xf bound_ctrl:1
	v_max_f32_e32 v43, v43, v43
	v_max_f32_e32 v42, v42, v43
	s_nop 1
	v_mov_b32_dpp v43, v42 row_mirror row_mask:0xf bank_mask:0xf bound_ctrl:1
	v_max_f32_e32 v43, v43, v43
	v_max_f32_e32 v42, v42, v43
	v_sub_f32_e32 v38, v38, v42
	v_mul_f32_e32 v38, 0x3fb8aa3b, v38
	v_exp_f32_e32 v38, v38
	s_nop 1
	v_add_f32_dpp v42, v38, v38 quad_perm:[1,0,3,2] row_mask:0xf bank_mask:0xf bound_ctrl:1
	s_nop 1
	v_add_f32_dpp v42, v42, v42 quad_perm:[2,3,0,1] row_mask:0xf bank_mask:0xf bound_ctrl:1
	s_nop 1
	v_add_f32_dpp v42, v42, v42 row_half_mirror row_mask:0xf bank_mask:0xf bound_ctrl:1
	s_nop 1
	v_mov_b32_dpp v43, v42 row_mirror row_mask:0xf bank_mask:0xf bound_ctrl:1
	s_and_saveexec_b64 s[26:27], vcc
	s_cbranch_execz .LBB0_2522
	v_add_f32_e32 v42, v42, v43
	v_rcp_f32_e32 v42, v42
	s_sub_i32 s19, s18, 24
	s_ashr_i32 s0, s19, 11
	s_ashr_i32 s1, s0, 31
	s_and_b32 s19, s19, 0x7ff
	s_lshl_b64 s[0:1], s[0:1], 17
	v_mul_f32_e32 v38, v38, v42
	v_lshl_add_u64 v[42:43], v[34:35], 0, s[0:1]
	s_lshl_b32 s22, s19, 2
	v_lshl_add_u64 v[42:43], v[42:43], 0, s[22:23]
	global_store_dword v[42:43], v38, off
.LBB0_2522:
	s_or_b64 exec, exec, s[26:27]
	v_mov_b32_dpp v38, v39 quad_perm:[1,0,3,2] row_mask:0xf bank_mask:0xf bound_ctrl:1
	v_max_f32_e32 v38, v38, v38
	v_max_f32_e32 v42, v39, v39
	v_max_f32_e32 v38, v42, v38
	v_pk_add_f32 v[36:37], v[36:37], v[40:41]
	v_pk_add_f32 v[40:41], v[44:45], v[48:49]
	v_mov_b32_dpp v42, v38 quad_perm:[2,3,0,1] row_mask:0xf bank_mask:0xf bound_ctrl:1
	v_max_f32_e32 v42, v42, v42
	v_max_f32_e32 v38, v38, v42
	v_pk_add_f32 v[36:37], v[36:37], v[40:41]
	s_nop 0
	v_mov_b32_dpp v42, v38 row_half_mirror row_mask:0xf bank_mask:0xf bound_ctrl:1
	v_max_f32_e32 v42, v42, v42
	v_max_f32_e32 v38, v38, v42
	s_nop 1
	v_mov_b32_dpp v42, v38 row_mirror row_mask:0xf bank_mask:0xf bound_ctrl:1
	v_max_f32_e32 v42, v42, v42
	v_max_f32_e32 v38, v38, v42
	v_sub_f32_e32 v38, v39, v38
	v_mul_f32_e32 v38, 0x3fb8aa3b, v38
	v_exp_f32_e32 v38, v38
	s_nop 1
	v_add_f32_dpp v39, v38, v38 quad_perm:[1,0,3,2] row_mask:0xf bank_mask:0xf bound_ctrl:1
	s_nop 1
	v_add_f32_dpp v39, v39, v39 quad_perm:[2,3,0,1] row_mask:0xf bank_mask:0xf bound_ctrl:1
	s_nop 1
	v_add_f32_dpp v39, v39, v39 row_half_mirror row_mask:0xf bank_mask:0xf bound_ctrl:1
	s_nop 1
	v_mov_b32_dpp v40, v39 row_mirror row_mask:0xf bank_mask:0xf bound_ctrl:1
	s_and_saveexec_b64 s[26:27], vcc
	s_cbranch_execz .LBB0_2524
	v_add_f32_e32 v39, v39, v40
	v_rcp_f32_e32 v39, v39
	s_add_i32 s19, s18, -16
	s_ashr_i32 s0, s19, 11
	s_ashr_i32 s1, s0, 31
	s_and_b32 s19, s19, 0x7ff
	s_lshl_b64 s[0:1], s[0:1], 17
	v_mul_f32_e32 v40, v38, v39
	v_lshl_add_u64 v[38:39], v[34:35], 0, s[0:1]
	s_lshl_b32 s22, s19, 2
	v_lshl_add_u64 v[38:39], v[38:39], 0, s[22:23]
	global_store_dword v[38:39], v40, off
.LBB0_2524:
	s_or_b64 exec, exec, s[26:27]
	v_mov_b32_dpp v38, v36 quad_perm:[1,0,3,2] row_mask:0xf bank_mask:0xf bound_ctrl:1
	v_max_f32_e32 v38, v38, v38
	v_max_f32_e32 v39, v36, v36
	v_max_f32_e32 v38, v39, v38
	s_nop 1
	v_mov_b32_dpp v39, v38 quad_perm:[2,3,0,1] row_mask:0xf bank_mask:0xf bound_ctrl:1
	v_max_f32_e32 v39, v39, v39
	v_max_f32_e32 v38, v38, v39
	s_nop 1
	v_mov_b32_dpp v39, v38 row_half_mirror row_mask:0xf bank_mask:0xf bound_ctrl:1
	v_max_f32_e32 v39, v39, v39
	v_max_f32_e32 v38, v38, v39
	s_nop 1
	v_mov_b32_dpp v39, v38 row_mirror row_mask:0xf bank_mask:0xf bound_ctrl:1
	v_max_f32_e32 v39, v39, v39
	v_max_f32_e32 v38, v38, v39
	v_sub_f32_e32 v36, v36, v38
	v_mul_f32_e32 v36, 0x3fb8aa3b, v36
	v_exp_f32_e32 v36, v36
	s_nop 1
	v_add_f32_dpp v38, v36, v36 quad_perm:[1,0,3,2] row_mask:0xf bank_mask:0xf bound_ctrl:1
	s_nop 1
	v_add_f32_dpp v38, v38, v38 quad_perm:[2,3,0,1] row_mask:0xf bank_mask:0xf bound_ctrl:1
	s_nop 1
	v_add_f32_dpp v38, v38, v38 row_half_mirror row_mask:0xf bank_mask:0xf bound_ctrl:1
	s_nop 1
	v_mov_b32_dpp v39, v38 row_mirror row_mask:0xf bank_mask:0xf bound_ctrl:1
	s_and_saveexec_b64 s[26:27], vcc
	s_cbranch_execz .LBB0_2526
	v_add_f32_e32 v38, v38, v39
	v_rcp_f32_e32 v38, v38
	s_add_i32 s19, s18, -8
	s_ashr_i32 s0, s19, 11
	s_ashr_i32 s1, s0, 31
	s_and_b32 s19, s19, 0x7ff
	s_lshl_b64 s[0:1], s[0:1], 17
	v_mul_f32_e32 v36, v36, v38
	v_lshl_add_u64 v[38:39], v[34:35], 0, s[0:1]
	s_lshl_b32 s22, s19, 2
	v_lshl_add_u64 v[38:39], v[38:39], 0, s[22:23]
	global_store_dword v[38:39], v36, off
.LBB0_2526:
	s_or_b64 exec, exec, s[26:27]
	v_mov_b32_dpp v36, v37 quad_perm:[1,0,3,2] row_mask:0xf bank_mask:0xf bound_ctrl:1
	v_max_f32_e32 v36, v36, v36
	v_max_f32_e32 v38, v37, v37
	v_max_f32_e32 v36, v38, v36
	s_nop 1
	v_mov_b32_dpp v38, v36 quad_perm:[2,3,0,1] row_mask:0xf bank_mask:0xf bound_ctrl:1
	v_max_f32_e32 v38, v38, v38
	v_max_f32_e32 v36, v36, v38
	s_nop 1
	v_mov_b32_dpp v38, v36 row_half_mirror row_mask:0xf bank_mask:0xf bound_ctrl:1
	v_max_f32_e32 v38, v38, v38
	v_max_f32_e32 v36, v36, v38
	s_nop 1
	v_mov_b32_dpp v38, v36 row_mirror row_mask:0xf bank_mask:0xf bound_ctrl:1
	v_max_f32_e32 v38, v38, v38
	v_max_f32_e32 v36, v36, v38
	v_sub_f32_e32 v36, v37, v36
	v_mul_f32_e32 v36, 0x3fb8aa3b, v36
	v_exp_f32_e32 v36, v36
	s_nop 1
	v_add_f32_dpp v37, v36, v36 quad_perm:[1,0,3,2] row_mask:0xf bank_mask:0xf bound_ctrl:1
	s_nop 1
	v_add_f32_dpp v37, v37, v37 quad_perm:[2,3,0,1] row_mask:0xf bank_mask:0xf bound_ctrl:1
	s_nop 1
	v_add_f32_dpp v37, v37, v37 row_half_mirror row_mask:0xf bank_mask:0xf bound_ctrl:1
	s_nop 1
	v_mov_b32_dpp v38, v37 row_mirror row_mask:0xf bank_mask:0xf bound_ctrl:1
	s_and_saveexec_b64 s[26:27], vcc
	s_cbranch_execz .LBB0_2517
	v_add_f32_e32 v37, v37, v38
	v_rcp_f32_e32 v37, v37
	s_ashr_i32 s0, s18, 11
	s_ashr_i32 s1, s0, 31
	s_and_b32 s18, s18, 0x7ff
	s_lshl_b64 s[0:1], s[0:1], 17
	v_lshl_add_u64 v[34:35], v[34:35], 0, s[0:1]
	s_lshl_b32 s22, s18, 2
	v_mul_f32_e32 v36, v36, v37
	v_lshl_add_u64 v[34:35], v[34:35], 0, s[22:23]
	global_store_dword v[34:35], v36, off
	s_branch .LBB0_2517
